# nt cache policy on read-once streams: LN0 input rows, P4 gate loads, P5/P8 residual rows, final LN output stores
# baseline (speedup 1.0000x reference)
.LBB0_283:
	s_mov_b64 s[8:9], s[96:97]
	s_load_dwordx4 s[4:7], s[8:9], 0x0
	s_load_dwordx2 s[2:3], s[8:9], 0x10
	s_mov_b32 s13, s93
	s_mov_b32 s12, s94
	v_mov_b32_e32 v67, v192
	s_movk_i32 s11, 0x4000
	v_lshlrev_b32_e32 v2, 2, v67
	v_and_b32_e32 v68, 0xfc, v2
	v_lshlrev_b32_e32 v66, 2, v68
	v_or_b32_e32 v62, 0x1000, v66
	v_or_b32_e32 v63, 0x1400, v66
	v_or_b32_e32 v64, 0x1800, v66
	v_or_b32_e32 v65, 0x1c00, v66
	s_waitcnt lgkmcnt(0)
	global_load_dwordx4 v[2:5], v66, s[6:7] offset:3072 nt
	global_load_dwordx4 v[6:9], v66, s[6:7] offset:2048 nt
	global_load_dwordx4 v[10:13], v66, s[6:7] offset:1024 nt
	global_load_dwordx4 v[14:17], v66, s[6:7] nt
	global_load_dwordx4 v[18:21], v66, s[2:3] offset:3072 nt
	global_load_dwordx4 v[22:25], v66, s[2:3] offset:2048 nt
	global_load_dwordx4 v[26:29], v66, s[2:3] offset:1024 nt
	global_load_dwordx4 v[30:33], v66, s[2:3] nt
	global_load_dwordx4 v[34:37], v65, s[6:7] nt
	global_load_dwordx4 v[38:41], v65, s[2:3] nt
	global_load_dwordx4 v[42:45], v64, s[6:7] nt
	global_load_dwordx4 v[46:49], v64, s[2:3] nt
	global_load_dwordx4 v[50:53], v63, s[6:7] nt
	global_load_dwordx4 v[54:57], v63, s[2:3] nt
	global_load_dwordx4 v[58:61], v62, s[6:7] nt
	s_nop 0
	global_load_dwordx4 v[62:65], v62, s[2:3] nt
	v_ashrrev_i32_e32 v67, 6, v67
	v_lshl_add_u32 v136, s13, 3, v67
	s_movk_i32 s10, 0x1000
	v_cmp_gt_i32_e32 vcc, s11, v136
	s_waitcnt vmcnt(1)
	s_waitcnt vmcnt(0)
	s_and_saveexec_b64 s[2:3], vcc
	s_xor_b64 s[2:3], exec, s[2:3]
	s_cbranch_execz .LBB0_291
	s_load_dwordx2 s[6:7], s[8:9], 0xc8
	v_mov_b32_e32 v67, 0
	v_lshl_add_u64 v[130:131], s[4:5], 0, v[66:67]
	v_lshlrev_b32_e32 v66, 1, v68
	s_mov_b64 s[4:5], 0x7200000
	s_waitcnt lgkmcnt(0)
	v_lshl_add_u64 v[66:67], s[6:7], 0, v[66:67]
	v_lshl_add_u64 v[132:133], v[66:67], 0, s[4:5]
	v_mbcnt_hi_u32_b32 v66, -1, v1
	v_and_b32_e32 v67, 64, v66
	v_add_u32_e32 v67, 64, v67
	v_xor_b32_e32 v68, 32, v66
	v_cmp_lt_i32_e32 vcc, v68, v67
	s_lshl_b32 s12, s12, 3
	s_mov_b64 s[6:7], 0
	v_cndmask_b32_e32 v68, v66, v68, vcc
	v_lshlrev_b32_e32 v138, 2, v68
	v_xor_b32_e32 v68, 16, v66
	v_cmp_lt_i32_e32 vcc, v68, v67
	s_movk_i32 s13, 0x3fff
	v_mov_b32_e32 v144, 0x3727c5ac
	v_cndmask_b32_e32 v68, v66, v68, vcc
	v_lshlrev_b32_e32 v139, 2, v68
	v_xor_b32_e32 v68, 8, v66
	v_cmp_lt_i32_e32 vcc, v68, v67
	s_mov_b32 s14, 0x800000
	s_nop 0
	v_cndmask_b32_e32 v68, v66, v68, vcc
	v_lshlrev_b32_e32 v140, 2, v68
	v_xor_b32_e32 v68, 4, v66
	v_cmp_lt_i32_e32 vcc, v68, v67
	s_nop 1
	v_cndmask_b32_e32 v68, v66, v68, vcc
	v_lshlrev_b32_e32 v141, 2, v68
	v_xor_b32_e32 v68, 2, v66
	v_cmp_lt_i32_e32 vcc, v68, v67
	s_nop 1
	v_cndmask_b32_e32 v68, v66, v68, vcc
	v_lshlrev_b32_e32 v142, 2, v68
	v_xor_b32_e32 v68, 1, v66
	v_cmp_lt_i32_e32 vcc, v68, v67
	s_nop 1
	v_cndmask_b32_e32 v66, v66, v68, vcc
	v_lshlrev_b32_e32 v143, 2, v66
	s_branch .LBB0_286

.LBB0_286:
	v_ashrrev_i32_e32 v137, 31, v136
	v_lshlrev_b64 v[98:99], 13, v[136:137]
	v_lshl_add_u64 v[98:99], v[130:131], 0, v[98:99]
	v_add_co_u32_e32 v126, vcc, 0x1000, v98
	global_load_dwordx4 v[122:125], v[98:99], off nt
	global_load_dwordx4 v[118:121], v[98:99], off offset:1024 nt
	global_load_dwordx4 v[114:117], v[98:99], off offset:2048 nt
	global_load_dwordx4 v[110:113], v[98:99], off offset:3072 nt
	v_addc_co_u32_e32 v127, vcc, 0, v99, vcc
	global_load_dwordx4 v[106:109], v[126:127], off nt
	global_load_dwordx4 v[102:105], v[126:127], off offset:1024 nt
	global_load_dwordx4 v[98:101], v[126:127], off offset:2048 nt
	s_nop 0
	global_load_dwordx4 v[126:129], v[126:127], off offset:3072 nt
	v_add_u32_e32 v134, s12, v136
	v_cmp_lt_i32_e32 vcc, s13, v134
	v_cmp_gt_i32_e64 s[4:5], s11, v134
	v_ashrrev_i32_e32 v135, 31, v134
	s_and_saveexec_b64 s[8:9], s[4:5]
	s_cbranch_execz .LBB0_288
	v_lshlrev_b64 v[66:67], 13, v[134:135]
	v_lshl_add_u64 v[82:83], v[130:131], 0, v[66:67]
	v_add_co_u32_e64 v94, s[4:5], s10, v82
	global_load_dwordx4 v[66:69], v[82:83], off nt
	global_load_dwordx4 v[70:73], v[82:83], off offset:1024 nt
	global_load_dwordx4 v[74:77], v[82:83], off offset:2048 nt
	global_load_dwordx4 v[78:81], v[82:83], off offset:3072 nt
	v_addc_co_u32_e64 v95, s[4:5], 0, v83, s[4:5]
	global_load_dwordx4 v[82:85], v[94:95], off nt
	global_load_dwordx4 v[86:89], v[94:95], off offset:1024 nt
	global_load_dwordx4 v[90:93], v[94:95], off offset:2048 nt
	s_nop 0
	global_load_dwordx4 v[94:97], v[94:95], off offset:3072 nt

.LBB0_879:
	v_lshlrev_b64 v[128:129], 1, v[168:169]
	v_ashrrev_i32_e32 v167, 31, v166
	v_lshl_add_u64 v[152:153], s[46:47], 0, v[128:129]
	v_lshl_add_u64 v[154:155], s[54:55], 0, v[128:129]
	v_lshlrev_b64 v[128:129], 13, v[166:167]
	v_add_u32_e32 v168, 16, v166
	v_lshl_add_u64 v[128:129], v[154:155], 0, v[128:129]
	v_ashrrev_i32_e32 v169, 31, v168
	global_load_dwordx4 v[170:173], v[128:129], off nt
	global_load_dwordx4 v[178:181], v[128:129], off offset:256 nt
	v_lshlrev_b64 v[128:129], 13, v[168:169]
	v_add_u32_e32 v158, 32, v166
	v_lshl_add_u64 v[128:129], v[154:155], 0, v[128:129]
	v_ashrrev_i32_e32 v159, 31, v158
	global_load_dwordx4 v[148:151], v[128:129], off nt
	global_load_dwordx4 v[144:147], v[128:129], off offset:256 nt
	v_lshlrev_b64 v[128:129], 13, v[158:159]
	v_add_u32_e32 v156, 48, v166
	v_lshl_add_u64 v[128:129], v[154:155], 0, v[128:129]
	v_ashrrev_i32_e32 v157, 31, v156
	global_load_dwordx4 v[140:143], v[128:129], off nt
	global_load_dwordx4 v[136:139], v[128:129], off offset:256 nt
	v_lshlrev_b64 v[128:129], 13, v[156:157]
	v_lshl_add_u64 v[128:129], v[154:155], 0, v[128:129]
	global_load_dwordx4 v[132:135], v[128:129], off nt
	s_nop 0
	global_load_dwordx4 v[128:131], v[128:129], off offset:256 nt
	v_lshlrev_b64 v[182:183], 12, v[166:167]
	v_lshl_add_u64 v[182:183], v[152:153], 0, v[182:183]
	s_and_b64 vcc, exec, s[40:41]
	s_mov_b32 s3, s56
	s_mov_b32 s2, s58
	s_mov_b64 s[20:21], s[62:63]
	s_mov_b64 s[48:49], s[60:61]
	s_waitcnt vmcnt(0)
	s_nop 0
	v_lshlrev_b32_e32 v167, 16, v170
	v_mul_f32_e32 v124, v124, v167
	v_and_b32_e32 v167, 0xffff0000, v170
	v_mul_f32_e32 v125, v125, v167
	v_lshlrev_b32_e32 v167, 16, v171
	v_mul_f32_e32 v126, v126, v167
	v_and_b32_e32 v167, 0xffff0000, v171
	v_mul_f32_e32 v127, v127, v167
	v_lshlrev_b32_e32 v167, 16, v172
	v_mul_f32_e32 v167, v120, v167
	v_and_b32_e32 v120, 0xffff0000, v172
	v_mul_f32_e32 v170, v121, v120
	v_lshlrev_b32_e32 v120, 16, v173
	v_mul_f32_e32 v171, v122, v120
	v_and_b32_e32 v120, 0xffff0000, v173
	v_mul_f32_e32 v123, v123, v120
	v_cvt_pk_bf16_f32 v120, v124, v125
	v_cvt_pk_bf16_f32 v121, v126, v127
	v_cvt_pk_bf16_f32 v122, v167, v170
	v_cvt_pk_bf16_f32 v123, v171, v123
	global_store_dwordx4 v[182:183], v[120:123], off
	s_nop 1
	v_lshlrev_b32_e32 v120, 16, v178
	v_mul_f32_e32 v116, v116, v120
	v_and_b32_e32 v120, 0xffff0000, v178
	v_mul_f32_e32 v117, v117, v120
	v_lshlrev_b32_e32 v120, 16, v179
	v_mul_f32_e32 v118, v118, v120
	v_and_b32_e32 v120, 0xffff0000, v179
	v_mul_f32_e32 v119, v119, v120
	v_lshlrev_b32_e32 v120, 16, v180
	v_mul_f32_e32 v120, v112, v120
	v_and_b32_e32 v112, 0xffff0000, v180
	v_mul_f32_e32 v121, v113, v112
	v_lshlrev_b32_e32 v112, 16, v181
	v_mul_f32_e32 v122, v114, v112
	v_and_b32_e32 v112, 0xffff0000, v181
	v_mul_f32_e32 v115, v115, v112
	v_cvt_pk_bf16_f32 v112, v116, v117
	v_cvt_pk_bf16_f32 v113, v118, v119
	v_cvt_pk_bf16_f32 v114, v120, v121
	v_cvt_pk_bf16_f32 v115, v122, v115
	global_store_dwordx4 v[182:183], v[112:115], off offset:256
	s_nop 1
	v_lshlrev_b32_e32 v114, 16, v148
	v_mul_f32_e32 v108, v108, v114
	v_and_b32_e32 v114, 0xffff0000, v148
	v_mul_f32_e32 v109, v109, v114
	v_lshlrev_b32_e32 v114, 16, v149
	v_mul_f32_e32 v110, v110, v114
	v_and_b32_e32 v114, 0xffff0000, v149
	v_mul_f32_e32 v111, v111, v114
	v_lshlrev_b32_e32 v114, 16, v150
	v_mul_f32_e32 v114, v104, v114
	v_and_b32_e32 v104, 0xffff0000, v150
	v_mul_f32_e32 v115, v105, v104
	v_lshlrev_b32_e32 v104, 16, v151
	v_lshlrev_b64 v[112:113], 12, v[168:169]
	v_mul_f32_e32 v116, v106, v104
	v_and_b32_e32 v104, 0xffff0000, v151
	v_lshl_add_u64 v[112:113], v[152:153], 0, v[112:113]
	v_mul_f32_e32 v107, v107, v104
	v_cvt_pk_bf16_f32 v104, v108, v109
	v_cvt_pk_bf16_f32 v105, v110, v111
	v_cvt_pk_bf16_f32 v106, v114, v115
	v_cvt_pk_bf16_f32 v107, v116, v107
	global_store_dwordx4 v[112:113], v[104:107], off
	s_nop 1
	v_lshlrev_b32_e32 v104, 16, v144
	v_mul_f32_e32 v100, v100, v104
	v_and_b32_e32 v104, 0xffff0000, v144
	v_mul_f32_e32 v101, v101, v104
	v_lshlrev_b32_e32 v104, 16, v145
	v_mul_f32_e32 v102, v102, v104
	v_and_b32_e32 v104, 0xffff0000, v145
	v_mul_f32_e32 v103, v103, v104
	v_lshlrev_b32_e32 v104, 16, v146
	v_mul_f32_e32 v104, v92, v104
	v_and_b32_e32 v92, 0xffff0000, v146
	v_mul_f32_e32 v105, v93, v92
	v_lshlrev_b32_e32 v92, 16, v147
	v_mul_f32_e32 v106, v94, v92
	v_and_b32_e32 v92, 0xffff0000, v147
	v_mul_f32_e32 v95, v95, v92
	v_cvt_pk_bf16_f32 v92, v100, v101
	v_cvt_pk_bf16_f32 v93, v102, v103
	v_cvt_pk_bf16_f32 v94, v104, v105
	v_cvt_pk_bf16_f32 v95, v106, v95
	global_store_dwordx4 v[112:113], v[92:95], off offset:256
	v_add_u32_e32 v102, 0xb0, v166
	v_ashrrev_i32_e32 v103, 31, v102
	v_lshlrev_b32_e32 v94, 16, v140
	v_mul_f32_e32 v94, v96, v94
	v_lshlrev_b32_e32 v96, 16, v141
	v_and_b32_e32 v95, 0xffff0000, v140
	v_mul_f32_e32 v96, v98, v96
	v_lshlrev_b32_e32 v98, 16, v142
	v_mul_f32_e32 v95, v97, v95
	v_and_b32_e32 v97, 0xffff0000, v141
	v_mul_f32_e32 v98, v88, v98
	v_and_b32_e32 v88, 0xffff0000, v142
	v_mul_f32_e32 v97, v99, v97
	v_mul_f32_e32 v99, v89, v88
	v_lshlrev_b32_e32 v88, 16, v143
	v_lshlrev_b64 v[92:93], 12, v[158:159]
	v_mul_f32_e32 v100, v90, v88
	v_and_b32_e32 v88, 0xffff0000, v143
	v_lshl_add_u64 v[92:93], v[152:153], 0, v[92:93]
	v_mul_f32_e32 v91, v91, v88
	v_cvt_pk_bf16_f32 v88, v94, v95
	v_cvt_pk_bf16_f32 v89, v96, v97
	v_cvt_pk_bf16_f32 v90, v98, v99
	v_cvt_pk_bf16_f32 v91, v100, v91
	global_store_dwordx4 v[92:93], v[88:91], off
	v_add_u32_e32 v96, 0x80, v166
	v_add_u32_e32 v98, 0x90, v166
	v_lshlrev_b32_e32 v88, 16, v136
	v_mul_f32_e32 v84, v84, v88
	v_and_b32_e32 v88, 0xffff0000, v136
	v_mul_f32_e32 v85, v85, v88
	v_lshlrev_b32_e32 v88, 16, v137
	v_mul_f32_e32 v86, v86, v88
	v_and_b32_e32 v88, 0xffff0000, v137
	v_mul_f32_e32 v87, v87, v88
	v_lshlrev_b32_e32 v88, 16, v138
	v_mul_f32_e32 v88, v76, v88
	v_and_b32_e32 v76, 0xffff0000, v138
	v_mul_f32_e32 v89, v77, v76
	v_lshlrev_b32_e32 v76, 16, v139
	v_mul_f32_e32 v90, v78, v76
	v_and_b32_e32 v76, 0xffff0000, v139
	v_mul_f32_e32 v79, v79, v76
	v_cvt_pk_bf16_f32 v76, v84, v85
	v_cvt_pk_bf16_f32 v77, v86, v87
	v_cvt_pk_bf16_f32 v78, v88, v89
	v_cvt_pk_bf16_f32 v79, v90, v79
	global_store_dwordx4 v[92:93], v[76:79], off offset:256
	v_add_u32_e32 v100, 0xa0, v166
	v_ashrrev_i32_e32 v97, 31, v96
	v_lshlrev_b32_e32 v78, 16, v132
	v_mul_f32_e32 v78, v80, v78
	v_lshlrev_b32_e32 v80, 16, v133
	v_and_b32_e32 v79, 0xffff0000, v132
	v_mul_f32_e32 v80, v82, v80
	v_lshlrev_b32_e32 v82, 16, v134
	v_mul_f32_e32 v79, v81, v79
	v_and_b32_e32 v81, 0xffff0000, v133
	v_mul_f32_e32 v82, v72, v82
	v_and_b32_e32 v72, 0xffff0000, v134
	v_mul_f32_e32 v81, v83, v81
	v_mul_f32_e32 v83, v73, v72
	v_lshlrev_b32_e32 v72, 16, v135
	v_lshlrev_b64 v[76:77], 12, v[156:157]
	v_mul_f32_e32 v84, v74, v72
	v_and_b32_e32 v72, 0xffff0000, v135
	v_lshl_add_u64 v[76:77], v[152:153], 0, v[76:77]
	v_mul_f32_e32 v75, v75, v72
	v_cvt_pk_bf16_f32 v72, v78, v79
	v_cvt_pk_bf16_f32 v73, v80, v81
	v_cvt_pk_bf16_f32 v74, v82, v83
	v_cvt_pk_bf16_f32 v75, v84, v75
	global_store_dwordx4 v[76:77], v[72:75], off
	v_ashrrev_i32_e32 v99, 31, v98
	v_ashrrev_i32_e32 v101, 31, v100
	v_lshlrev_b32_e32 v72, 16, v128
	v_mul_f32_e32 v68, v68, v72
	v_and_b32_e32 v72, 0xffff0000, v128
	v_mul_f32_e32 v69, v69, v72
	v_lshlrev_b32_e32 v72, 16, v129
	v_mul_f32_e32 v70, v70, v72
	v_and_b32_e32 v72, 0xffff0000, v129
	v_mul_f32_e32 v71, v71, v72
	v_lshlrev_b32_e32 v72, 16, v130
	v_mul_f32_e32 v72, v64, v72
	v_and_b32_e32 v64, 0xffff0000, v130
	v_mul_f32_e32 v73, v65, v64
	v_lshlrev_b32_e32 v64, 16, v131
	v_mul_f32_e32 v74, v66, v64
	v_and_b32_e32 v64, 0xffff0000, v131
	v_mul_f32_e32 v67, v67, v64
	v_cvt_pk_bf16_f32 v64, v68, v69
	v_cvt_pk_bf16_f32 v65, v70, v71
	v_cvt_pk_bf16_f32 v66, v72, v73
	v_cvt_pk_bf16_f32 v67, v74, v67
	global_store_dwordx4 v[76:77], v[64:67], off offset:256
	v_lshlrev_b64 v[72:73], 13, v[98:99]
	v_lshlrev_b64 v[80:81], 13, v[100:101]
	v_lshlrev_b64 v[64:65], 13, v[96:97]
	v_lshlrev_b64 v[88:89], 13, v[102:103]
	v_lshl_add_u64 v[68:69], v[154:155], 0, v[64:65]
	v_lshl_add_u64 v[76:77], v[154:155], 0, v[72:73]
	v_lshl_add_u64 v[84:85], v[154:155], 0, v[80:81]
	v_lshl_add_u64 v[92:93], v[154:155], 0, v[88:89]
	global_load_dwordx4 v[64:67], v[68:69], off nt
	s_nop 0
	global_load_dwordx4 v[68:71], v[68:69], off offset:256 nt
	s_nop 0
	global_load_dwordx4 v[72:75], v[76:77], off nt
	s_nop 0
	global_load_dwordx4 v[76:79], v[76:77], off offset:256 nt
	s_nop 0
	global_load_dwordx4 v[80:83], v[84:85], off nt
	s_nop 0
	global_load_dwordx4 v[84:87], v[84:85], off offset:256 nt
	s_nop 0
	global_load_dwordx4 v[88:91], v[92:93], off nt
	s_nop 0
	global_load_dwordx4 v[92:95], v[92:93], off offset:256 nt
	s_waitcnt vmcnt(0)
	s_nop 0
	v_lshlrev_b32_e32 v104, 16, v64
	v_and_b32_e32 v64, 0xffff0000, v64
	v_mul_f32_e32 v61, v61, v64
	v_lshlrev_b32_e32 v64, 16, v65
	v_mul_f32_e32 v62, v62, v64
	v_and_b32_e32 v64, 0xffff0000, v65
	v_mul_f32_e32 v63, v63, v64
	v_lshlrev_b32_e32 v64, 16, v66
	v_mul_f32_e32 v64, v56, v64
	v_and_b32_e32 v56, 0xffff0000, v66
	v_mul_f32_e32 v65, v57, v56
	v_lshlrev_b32_e32 v56, 16, v67
	v_lshlrev_b64 v[96:97], 12, v[96:97]
	v_mul_f32_e32 v66, v58, v56
	v_and_b32_e32 v56, 0xffff0000, v67
	v_lshl_add_u64 v[96:97], v[152:153], 0, v[96:97]
	v_mul_f32_e32 v60, v60, v104
	v_mul_f32_e32 v59, v59, v56
	v_cvt_pk_bf16_f32 v56, v60, v61
	v_cvt_pk_bf16_f32 v57, v62, v63
	v_cvt_pk_bf16_f32 v58, v64, v65
	v_cvt_pk_bf16_f32 v59, v66, v59
	global_store_dwordx4 v[96:97], v[56:59], off
	s_nop 1
	v_lshlrev_b32_e32 v56, 16, v68
	v_mul_f32_e32 v52, v52, v56
	v_and_b32_e32 v56, 0xffff0000, v68
	v_mul_f32_e32 v53, v53, v56
	v_lshlrev_b32_e32 v56, 16, v69
	v_mul_f32_e32 v54, v54, v56
	v_and_b32_e32 v56, 0xffff0000, v69
	v_mul_f32_e32 v55, v55, v56
	v_lshlrev_b32_e32 v56, 16, v70
	v_mul_f32_e32 v56, v44, v56
	v_and_b32_e32 v44, 0xffff0000, v70
	v_mul_f32_e32 v57, v45, v44
	v_lshlrev_b32_e32 v44, 16, v71
	v_mul_f32_e32 v58, v46, v44
	v_and_b32_e32 v44, 0xffff0000, v71
	v_mul_f32_e32 v47, v47, v44
	v_cvt_pk_bf16_f32 v44, v52, v53
	v_cvt_pk_bf16_f32 v45, v54, v55
	v_cvt_pk_bf16_f32 v46, v56, v57
	v_cvt_pk_bf16_f32 v47, v58, v47
	global_store_dwordx4 v[96:97], v[44:47], off offset:256
	s_nop 1
	v_lshlrev_b32_e32 v46, 16, v72
	v_mul_f32_e32 v46, v48, v46
	v_lshlrev_b32_e32 v48, 16, v73
	v_and_b32_e32 v47, 0xffff0000, v72
	v_mul_f32_e32 v48, v50, v48
	v_lshlrev_b32_e32 v50, 16, v74
	v_mul_f32_e32 v47, v49, v47
	v_and_b32_e32 v49, 0xffff0000, v73
	v_mul_f32_e32 v50, v40, v50
	v_and_b32_e32 v40, 0xffff0000, v74
	v_mul_f32_e32 v49, v51, v49
	v_mul_f32_e32 v51, v41, v40
	v_lshlrev_b32_e32 v40, 16, v75
	v_lshlrev_b64 v[44:45], 12, v[98:99]
	v_mul_f32_e32 v52, v42, v40
	v_and_b32_e32 v40, 0xffff0000, v75
	v_lshl_add_u64 v[44:45], v[152:153], 0, v[44:45]
	v_mul_f32_e32 v43, v43, v40
	v_cvt_pk_bf16_f32 v40, v46, v47
	v_cvt_pk_bf16_f32 v41, v48, v49
	v_cvt_pk_bf16_f32 v42, v50, v51
	v_cvt_pk_bf16_f32 v43, v52, v43
	global_store_dwordx4 v[44:45], v[40:43], off
	s_nop 1
	v_lshlrev_b32_e32 v40, 16, v76
	v_mul_f32_e32 v36, v36, v40
	v_and_b32_e32 v40, 0xffff0000, v76
	v_mul_f32_e32 v37, v37, v40
	v_lshlrev_b32_e32 v40, 16, v77
	v_mul_f32_e32 v38, v38, v40
	v_and_b32_e32 v40, 0xffff0000, v77
	v_mul_f32_e32 v39, v39, v40
	v_lshlrev_b32_e32 v40, 16, v78
	v_mul_f32_e32 v40, v28, v40
	v_and_b32_e32 v28, 0xffff0000, v78
	v_mul_f32_e32 v41, v29, v28
	v_lshlrev_b32_e32 v28, 16, v79
	v_mul_f32_e32 v42, v30, v28
	v_and_b32_e32 v28, 0xffff0000, v79
	v_mul_f32_e32 v31, v31, v28
	v_cvt_pk_bf16_f32 v28, v36, v37
	v_cvt_pk_bf16_f32 v29, v38, v39
	v_cvt_pk_bf16_f32 v30, v40, v41
	v_cvt_pk_bf16_f32 v31, v42, v31
	global_store_dwordx4 v[44:45], v[28:31], off offset:256
	s_nop 1
	v_lshlrev_b32_e32 v30, 16, v80
	v_mul_f32_e32 v30, v32, v30
	v_lshlrev_b32_e32 v32, 16, v81
	v_and_b32_e32 v31, 0xffff0000, v80
	v_mul_f32_e32 v32, v34, v32
	v_lshlrev_b32_e32 v34, 16, v82
	v_mul_f32_e32 v31, v33, v31
	v_and_b32_e32 v33, 0xffff0000, v81
	v_mul_f32_e32 v34, v24, v34
	v_and_b32_e32 v24, 0xffff0000, v82
	v_mul_f32_e32 v33, v35, v33
	v_mul_f32_e32 v35, v25, v24
	v_lshlrev_b32_e32 v24, 16, v83
	v_lshlrev_b64 v[28:29], 12, v[100:101]
	v_mul_f32_e32 v36, v26, v24
	v_and_b32_e32 v24, 0xffff0000, v83
	v_lshl_add_u64 v[28:29], v[152:153], 0, v[28:29]
	v_mul_f32_e32 v27, v27, v24
	v_cvt_pk_bf16_f32 v24, v30, v31
	v_cvt_pk_bf16_f32 v25, v32, v33
	v_cvt_pk_bf16_f32 v26, v34, v35
	v_cvt_pk_bf16_f32 v27, v36, v27
	global_store_dwordx4 v[28:29], v[24:27], off
	s_nop 1
	v_lshlrev_b32_e32 v24, 16, v84
	v_mul_f32_e32 v20, v20, v24
	v_and_b32_e32 v24, 0xffff0000, v84
	v_mul_f32_e32 v21, v21, v24
	v_lshlrev_b32_e32 v24, 16, v85
	v_mul_f32_e32 v22, v22, v24
	v_and_b32_e32 v24, 0xffff0000, v85
	v_mul_f32_e32 v23, v23, v24
	v_lshlrev_b32_e32 v24, 16, v86
	v_mul_f32_e32 v24, v12, v24
	v_and_b32_e32 v12, 0xffff0000, v86
	v_mul_f32_e32 v25, v13, v12
	v_lshlrev_b32_e32 v12, 16, v87
	v_mul_f32_e32 v26, v14, v12
	v_and_b32_e32 v12, 0xffff0000, v87
	v_mul_f32_e32 v15, v15, v12
	v_cvt_pk_bf16_f32 v12, v20, v21
	v_cvt_pk_bf16_f32 v13, v22, v23
	v_cvt_pk_bf16_f32 v14, v24, v25
	v_cvt_pk_bf16_f32 v15, v26, v15
	global_store_dwordx4 v[28:29], v[12:15], off offset:256
	s_nop 1
	v_lshlrev_b32_e32 v14, 16, v88
	v_mul_f32_e32 v14, v16, v14
	v_lshlrev_b32_e32 v16, 16, v89
	v_and_b32_e32 v15, 0xffff0000, v88
	v_mul_f32_e32 v16, v18, v16
	v_lshlrev_b32_e32 v18, 16, v90
	v_mul_f32_e32 v15, v17, v15
	v_and_b32_e32 v17, 0xffff0000, v89
	v_mul_f32_e32 v18, v8, v18
	v_and_b32_e32 v8, 0xffff0000, v90
	v_mul_f32_e32 v17, v19, v17
	v_mul_f32_e32 v19, v9, v8
	v_lshlrev_b32_e32 v8, 16, v91
	v_lshlrev_b64 v[12:13], 12, v[102:103]
	v_mul_f32_e32 v20, v10, v8
	v_and_b32_e32 v8, 0xffff0000, v91
	v_lshl_add_u64 v[12:13], v[152:153], 0, v[12:13]
	v_mul_f32_e32 v11, v11, v8
	v_cvt_pk_bf16_f32 v8, v14, v15
	v_cvt_pk_bf16_f32 v9, v16, v17
	v_cvt_pk_bf16_f32 v10, v18, v19
	v_cvt_pk_bf16_f32 v11, v20, v11
	global_store_dwordx4 v[12:13], v[8:11], off
	s_nop 1
	v_lshlrev_b32_e32 v8, 16, v92
	v_mul_f32_e32 v4, v4, v8
	v_and_b32_e32 v8, 0xffff0000, v92
	v_mul_f32_e32 v5, v5, v8
	v_lshlrev_b32_e32 v8, 16, v93
	v_mul_f32_e32 v6, v6, v8
	v_and_b32_e32 v8, 0xffff0000, v93
	v_mul_f32_e32 v7, v7, v8
	v_lshlrev_b32_e32 v8, 16, v94
	v_mul_f32_e32 v8, v0, v8
	v_and_b32_e32 v0, 0xffff0000, v94
	v_mul_f32_e32 v9, v1, v0
	v_lshlrev_b32_e32 v0, 16, v95
	v_mul_f32_e32 v10, v2, v0
	v_and_b32_e32 v0, 0xffff0000, v95
	v_mul_f32_e32 v3, v3, v0
	v_cvt_pk_bf16_f32 v0, v4, v5
	v_cvt_pk_bf16_f32 v1, v6, v7
	v_cvt_pk_bf16_f32 v2, v8, v9
	v_cvt_pk_bf16_f32 v3, v10, v3
	global_store_dwordx4 v[12:13], v[0:3], off offset:256
	s_cbranch_vccnz .LBB0_900

.LBB0_899:
	v_mov_b32_e32 v170, v166
	v_lshlrev_b64 v[172:173], 1, v[168:169]
	v_ashrrev_i32_e32 v171, 31, v170
	v_lshlrev_b64 v[128:129], 13, v[170:171]
	v_add_u32_e32 v144, 16, v170
	v_lshl_add_u64 v[128:129], s[50:51], 0, v[128:129]
	v_ashrrev_i32_e32 v145, 31, v144
	v_lshl_add_u64 v[136:137], v[128:129], 0, v[172:173]
	v_lshlrev_b64 v[144:145], 13, v[144:145]
	v_add_co_u32_e32 v132, vcc, 0x1000, v136
	v_lshl_add_u64 v[144:145], s[50:51], 0, v[144:145]
	s_nop 0
	v_addc_co_u32_e32 v133, vcc, 0, v137, vcc
	v_lshl_add_u64 v[152:153], v[144:145], 0, v[172:173]
	v_add_co_u32_e32 v148, vcc, s81, v152
	v_lshl_add_u64 v[140:141], v[136:137], 0, s[72:73]
	v_lshl_add_u64 v[156:157], v[152:153], 0, s[72:73]
	v_addc_co_u32_e32 v149, vcc, 0, v153, vcc
	global_load_dwordx4 v[128:131], v[136:137], off nt
	s_nop 0
	global_load_dwordx4 v[132:135], v[132:133], off nt
	s_nop 0
	global_load_dwordx4 v[136:139], v[136:137], off offset:256 nt
	s_nop 0
	global_load_dwordx4 v[140:143], v[140:141], off offset:256 nt
	s_nop 0
	global_load_dwordx4 v[144:147], v[152:153], off nt
	s_nop 0
	global_load_dwordx4 v[148:151], v[148:149], off nt
	s_nop 0
	global_load_dwordx4 v[152:155], v[152:153], off offset:256 nt
	s_nop 0
	global_load_dwordx4 v[156:159], v[156:157], off offset:256 nt
	s_waitcnt vmcnt(0)
	s_nop 0
	v_lshlrev_b32_e32 v167, 16, v132
	v_and_b32_e32 v132, 0xffff0000, v132
	v_lshlrev_b32_e32 v180, 16, v128
	v_and_b32_e32 v181, 0xffff0000, v128
	v_lshlrev_b32_e32 v128, 16, v133
	v_rcp_f32_e32 v179, v132
	v_rcp_f32_e32 v132, v128
	v_and_b32_e32 v128, 0xffff0000, v133
	v_rcp_f32_e32 v133, v128
	v_lshlrev_b32_e32 v128, 16, v129
	v_and_b32_e32 v129, 0xffff0000, v129
	v_rcp_f32_e32 v178, v167
	v_pk_mul_f32 v[128:129], v[132:133], v[128:129]
	v_lshlrev_b32_e32 v132, 16, v130
	v_pk_mul_f32 v[126:127], v[126:127], v[128:129]
	v_lshlrev_b32_e32 v128, 16, v134
	v_and_b32_e32 v129, 0xffff0000, v134
	v_rcp_f32_e32 v128, v128
	v_rcp_f32_e32 v129, v129
	v_and_b32_e32 v133, 0xffff0000, v130
	v_lshlrev_b32_e32 v130, 16, v131
	v_and_b32_e32 v131, 0xffff0000, v131
	v_pk_mul_f32 v[128:129], v[128:129], v[132:133]
	v_pk_mul_f32 v[178:179], v[178:179], v[180:181]
	v_pk_mul_f32 v[120:121], v[120:121], v[128:129]
	v_lshlrev_b32_e32 v128, 16, v135
	v_and_b32_e32 v129, 0xffff0000, v135
	v_rcp_f32_e32 v128, v128
	v_rcp_f32_e32 v129, v129
	v_pk_mul_f32 v[124:125], v[124:125], v[178:179]
	v_pk_mul_f32 v[128:129], v[128:129], v[130:131]
	s_nop 0
	v_pk_mul_f32 v[122:123], v[122:123], v[128:129]
	v_lshlrev_b32_e32 v128, 16, v140
	v_and_b32_e32 v129, 0xffff0000, v140
	v_rcp_f32_e32 v128, v128
	v_rcp_f32_e32 v129, v129
	v_lshlrev_b32_e32 v130, 16, v136
	v_and_b32_e32 v131, 0xffff0000, v136
	v_pk_mul_f32 v[128:129], v[128:129], v[130:131]
	s_nop 0
	v_pk_mul_f32 v[116:117], v[116:117], v[128:129]
	v_lshlrev_b32_e32 v128, 16, v141
	v_and_b32_e32 v129, 0xffff0000, v141
	v_rcp_f32_e32 v128, v128
	v_rcp_f32_e32 v129, v129
	v_lshlrev_b32_e32 v130, 16, v137
	v_and_b32_e32 v131, 0xffff0000, v137
	v_pk_mul_f32 v[128:129], v[128:129], v[130:131]
	s_nop 0
	v_pk_mul_f32 v[118:119], v[118:119], v[128:129]
	v_lshlrev_b32_e32 v128, 16, v142
	v_and_b32_e32 v129, 0xffff0000, v142
	v_rcp_f32_e32 v128, v128
	v_rcp_f32_e32 v129, v129
	v_lshlrev_b32_e32 v130, 16, v138
	v_and_b32_e32 v131, 0xffff0000, v138
	v_pk_mul_f32 v[128:129], v[128:129], v[130:131]
	s_nop 0
	v_pk_mul_f32 v[112:113], v[112:113], v[128:129]
	v_lshlrev_b32_e32 v128, 16, v143
	v_and_b32_e32 v129, 0xffff0000, v143
	v_rcp_f32_e32 v128, v128
	v_rcp_f32_e32 v129, v129
	v_lshlrev_b32_e32 v130, 16, v139
	v_and_b32_e32 v131, 0xffff0000, v139
	v_pk_mul_f32 v[128:129], v[128:129], v[130:131]
	s_nop 0
	v_pk_mul_f32 v[114:115], v[114:115], v[128:129]
	v_lshlrev_b32_e32 v128, 16, v148
	v_and_b32_e32 v129, 0xffff0000, v148
	v_rcp_f32_e32 v128, v128
	v_rcp_f32_e32 v129, v129
	v_lshlrev_b32_e32 v130, 16, v144
	v_and_b32_e32 v131, 0xffff0000, v144
	v_add_u32_e32 v144, 48, v170
	v_pk_mul_f32 v[128:129], v[128:129], v[130:131]
	v_lshlrev_b32_e32 v130, 16, v145
	v_pk_mul_f32 v[108:109], v[108:109], v[128:129]
	v_lshlrev_b32_e32 v128, 16, v149
	v_and_b32_e32 v129, 0xffff0000, v149
	v_rcp_f32_e32 v128, v128
	v_rcp_f32_e32 v129, v129
	v_and_b32_e32 v131, 0xffff0000, v145
	v_ashrrev_i32_e32 v145, 31, v144
	v_lshlrev_b64 v[144:145], 13, v[144:145]
	v_pk_mul_f32 v[128:129], v[128:129], v[130:131]
	v_lshlrev_b32_e32 v130, 16, v146
	v_pk_mul_f32 v[110:111], v[110:111], v[128:129]
	v_lshlrev_b32_e32 v128, 16, v150
	v_and_b32_e32 v129, 0xffff0000, v150
	v_rcp_f32_e32 v128, v128
	v_rcp_f32_e32 v129, v129
	v_and_b32_e32 v131, 0xffff0000, v146
	v_lshl_add_u64 v[144:145], s[50:51], 0, v[144:145]
	v_lshl_add_u64 v[144:145], v[144:145], 0, v[172:173]
	v_pk_mul_f32 v[128:129], v[128:129], v[130:131]
	v_lshlrev_b32_e32 v130, 16, v147
	v_pk_mul_f32 v[104:105], v[104:105], v[128:129]
	v_lshlrev_b32_e32 v128, 16, v151
	v_and_b32_e32 v129, 0xffff0000, v151
	v_rcp_f32_e32 v128, v128
	v_rcp_f32_e32 v129, v129
	v_and_b32_e32 v131, 0xffff0000, v147
	v_lshl_add_u64 v[148:149], v[144:145], 0, s[72:73]
	v_pk_mul_f32 v[128:129], v[128:129], v[130:131]
	s_nop 0
	v_pk_mul_f32 v[106:107], v[106:107], v[128:129]
	v_lshlrev_b32_e32 v128, 16, v156
	v_and_b32_e32 v129, 0xffff0000, v156
	v_rcp_f32_e32 v128, v128
	v_rcp_f32_e32 v129, v129
	v_lshlrev_b32_e32 v130, 16, v152
	v_and_b32_e32 v131, 0xffff0000, v152
	v_pk_mul_f32 v[128:129], v[128:129], v[130:131]
	s_nop 0
	v_pk_mul_f32 v[100:101], v[100:101], v[128:129]
	v_lshlrev_b32_e32 v128, 16, v157
	v_and_b32_e32 v129, 0xffff0000, v157
	v_rcp_f32_e32 v128, v128
	v_rcp_f32_e32 v129, v129
	v_lshlrev_b32_e32 v130, 16, v153
	v_and_b32_e32 v131, 0xffff0000, v153
	v_pk_mul_f32 v[128:129], v[128:129], v[130:131]
	s_nop 0
	v_pk_mul_f32 v[102:103], v[102:103], v[128:129]
	v_lshlrev_b32_e32 v128, 16, v158
	v_and_b32_e32 v129, 0xffff0000, v158
	v_rcp_f32_e32 v128, v128
	v_rcp_f32_e32 v129, v129
	v_lshlrev_b32_e32 v130, 16, v154
	v_and_b32_e32 v131, 0xffff0000, v154
	v_pk_mul_f32 v[128:129], v[128:129], v[130:131]
	s_nop 0
	v_pk_mul_f32 v[92:93], v[92:93], v[128:129]
	v_lshlrev_b32_e32 v128, 16, v159
	v_and_b32_e32 v129, 0xffff0000, v159
	v_rcp_f32_e32 v128, v128
	v_rcp_f32_e32 v129, v129
	v_lshlrev_b32_e32 v130, 16, v155
	v_and_b32_e32 v131, 0xffff0000, v155
	v_pk_mul_f32 v[128:129], v[128:129], v[130:131]
	s_nop 0
	v_pk_mul_f32 v[94:95], v[94:95], v[128:129]
	v_add_u32_e32 v128, 32, v170
	v_ashrrev_i32_e32 v129, 31, v128
	v_lshlrev_b64 v[128:129], 13, v[128:129]
	v_lshl_add_u64 v[128:129], s[50:51], 0, v[128:129]
	v_lshl_add_u64 v[128:129], v[128:129], 0, v[172:173]
	v_add_co_u32_e32 v130, vcc, s81, v128
	v_lshl_add_u64 v[132:133], v[128:129], 0, s[72:73]
	s_nop 0
	v_addc_co_u32_e32 v131, vcc, 0, v129, vcc
	v_add_co_u32_e32 v146, vcc, s81, v144
	global_load_dwordx4 v[136:139], v[128:129], off nt
	s_nop 0
	v_addc_co_u32_e32 v147, vcc, 0, v145, vcc
	global_load_dwordx4 v[140:143], v[130:131], off nt
	s_nop 0
	global_load_dwordx4 v[128:131], v[128:129], off offset:256 nt
	s_nop 0
	global_load_dwordx4 v[132:135], v[132:133], off offset:256 nt
	s_nop 0
	global_load_dwordx4 v[152:155], v[144:145], off nt
	global_load_dwordx4 v[156:159], v[146:147], off nt
	s_nop 0
	global_load_dwordx4 v[144:147], v[144:145], off offset:256 nt
	s_nop 0
	global_load_dwordx4 v[148:151], v[148:149], off offset:256 nt
	s_waitcnt vmcnt(0)
	s_nop 0
	v_lshlrev_b32_e32 v167, 16, v140
	v_and_b32_e32 v140, 0xffff0000, v140
	v_lshlrev_b32_e32 v180, 16, v136
	v_and_b32_e32 v181, 0xffff0000, v136
	v_lshlrev_b32_e32 v136, 16, v141
	v_rcp_f32_e32 v179, v140
	v_rcp_f32_e32 v140, v136
	v_and_b32_e32 v136, 0xffff0000, v141
	v_rcp_f32_e32 v141, v136
	v_lshlrev_b32_e32 v136, 16, v137
	v_and_b32_e32 v137, 0xffff0000, v137
	v_rcp_f32_e32 v178, v167
	v_pk_mul_f32 v[136:137], v[140:141], v[136:137]
	v_lshlrev_b32_e32 v140, 16, v138
	v_pk_mul_f32 v[98:99], v[98:99], v[136:137]
	v_lshlrev_b32_e32 v136, 16, v142
	v_and_b32_e32 v137, 0xffff0000, v142
	v_rcp_f32_e32 v136, v136
	v_rcp_f32_e32 v137, v137
	v_and_b32_e32 v141, 0xffff0000, v138
	v_lshlrev_b32_e32 v138, 16, v139
	v_and_b32_e32 v139, 0xffff0000, v139
	v_pk_mul_f32 v[136:137], v[136:137], v[140:141]
	v_pk_mul_f32 v[178:179], v[178:179], v[180:181]
	v_pk_mul_f32 v[88:89], v[88:89], v[136:137]
	v_lshlrev_b32_e32 v136, 16, v143
	v_and_b32_e32 v137, 0xffff0000, v143
	v_rcp_f32_e32 v136, v136
	v_rcp_f32_e32 v137, v137
	v_pk_mul_f32 v[96:97], v[96:97], v[178:179]
	v_pk_mul_f32 v[136:137], v[136:137], v[138:139]
	s_nop 0
	v_pk_mul_f32 v[90:91], v[90:91], v[136:137]
	v_lshlrev_b32_e32 v136, 16, v132
	v_and_b32_e32 v132, 0xffff0000, v132
	v_lshlrev_b32_e32 v138, 16, v128
	v_and_b32_e32 v139, 0xffff0000, v128
	v_lshlrev_b32_e32 v128, 16, v133
	v_rcp_f32_e32 v137, v132
	v_rcp_f32_e32 v132, v128
	v_and_b32_e32 v128, 0xffff0000, v133
	v_rcp_f32_e32 v133, v128
	v_lshlrev_b32_e32 v128, 16, v129
	v_and_b32_e32 v129, 0xffff0000, v129
	v_rcp_f32_e32 v136, v136
	v_pk_mul_f32 v[128:129], v[132:133], v[128:129]
	v_lshlrev_b32_e32 v132, 16, v130
	v_pk_mul_f32 v[86:87], v[86:87], v[128:129]
	v_lshlrev_b32_e32 v128, 16, v134
	v_and_b32_e32 v129, 0xffff0000, v134
	v_rcp_f32_e32 v128, v128
	v_rcp_f32_e32 v129, v129
	v_and_b32_e32 v133, 0xffff0000, v130
	v_lshlrev_b32_e32 v130, 16, v131
	v_and_b32_e32 v131, 0xffff0000, v131
	v_pk_mul_f32 v[128:129], v[128:129], v[132:133]
	v_pk_mul_f32 v[136:137], v[136:137], v[138:139]
	v_pk_mul_f32 v[76:77], v[76:77], v[128:129]
	v_lshlrev_b32_e32 v128, 16, v135
	v_and_b32_e32 v129, 0xffff0000, v135
	v_rcp_f32_e32 v128, v128
	v_rcp_f32_e32 v129, v129
	v_pk_mul_f32 v[84:85], v[84:85], v[136:137]
	v_pk_mul_f32 v[128:129], v[128:129], v[130:131]
	s_nop 0
	v_pk_mul_f32 v[78:79], v[78:79], v[128:129]
	v_lshlrev_b32_e32 v128, 16, v156
	v_and_b32_e32 v129, 0xffff0000, v156
	v_rcp_f32_e32 v128, v128
	v_rcp_f32_e32 v129, v129
	v_lshlrev_b32_e32 v130, 16, v152
	v_and_b32_e32 v131, 0xffff0000, v152
	v_pk_mul_f32 v[128:129], v[128:129], v[130:131]
	s_nop 0
	v_pk_mul_f32 v[80:81], v[80:81], v[128:129]
	v_lshlrev_b32_e32 v128, 16, v157
	v_and_b32_e32 v129, 0xffff0000, v157
	v_rcp_f32_e32 v128, v128
	v_rcp_f32_e32 v129, v129
	v_lshlrev_b32_e32 v130, 16, v153
	v_and_b32_e32 v131, 0xffff0000, v153
	v_pk_mul_f32 v[128:129], v[128:129], v[130:131]
	s_nop 0
	v_pk_mul_f32 v[82:83], v[82:83], v[128:129]
	v_lshlrev_b32_e32 v128, 16, v158
	v_and_b32_e32 v129, 0xffff0000, v158
	v_rcp_f32_e32 v128, v128
	v_rcp_f32_e32 v129, v129
	v_lshlrev_b32_e32 v130, 16, v154
	v_and_b32_e32 v131, 0xffff0000, v154
	v_pk_mul_f32 v[128:129], v[128:129], v[130:131]
	s_nop 0
	v_pk_mul_f32 v[72:73], v[72:73], v[128:129]
	v_lshlrev_b32_e32 v128, 16, v159
	v_and_b32_e32 v129, 0xffff0000, v159
	v_rcp_f32_e32 v128, v128
	v_rcp_f32_e32 v129, v129
	v_lshlrev_b32_e32 v130, 16, v155
	v_and_b32_e32 v131, 0xffff0000, v155
	v_pk_mul_f32 v[128:129], v[128:129], v[130:131]
	s_nop 0
	v_pk_mul_f32 v[74:75], v[74:75], v[128:129]
	v_lshlrev_b32_e32 v128, 16, v148
	v_and_b32_e32 v129, 0xffff0000, v148
	v_rcp_f32_e32 v128, v128
	v_rcp_f32_e32 v129, v129
	v_lshlrev_b32_e32 v130, 16, v144
	v_and_b32_e32 v131, 0xffff0000, v144
	v_pk_mul_f32 v[128:129], v[128:129], v[130:131]
	s_nop 0
	v_pk_mul_f32 v[68:69], v[68:69], v[128:129]
	v_lshlrev_b32_e32 v128, 16, v149
	v_and_b32_e32 v129, 0xffff0000, v149
	v_rcp_f32_e32 v128, v128
	v_rcp_f32_e32 v129, v129
	v_lshlrev_b32_e32 v130, 16, v145
	v_and_b32_e32 v131, 0xffff0000, v145
	v_pk_mul_f32 v[128:129], v[128:129], v[130:131]
	s_nop 0
	v_pk_mul_f32 v[70:71], v[70:71], v[128:129]
	v_lshlrev_b32_e32 v128, 16, v150
	v_and_b32_e32 v129, 0xffff0000, v150
	v_rcp_f32_e32 v128, v128
	v_rcp_f32_e32 v129, v129
	v_lshlrev_b32_e32 v130, 16, v146
	v_and_b32_e32 v131, 0xffff0000, v146
	v_pk_mul_f32 v[128:129], v[128:129], v[130:131]
	s_nop 0
	v_pk_mul_f32 v[64:65], v[64:65], v[128:129]
	v_lshlrev_b32_e32 v128, 16, v151
	v_and_b32_e32 v129, 0xffff0000, v151
	v_rcp_f32_e32 v128, v128
	v_rcp_f32_e32 v129, v129
	v_lshlrev_b32_e32 v130, 16, v147
	v_and_b32_e32 v131, 0xffff0000, v147
	v_pk_mul_f32 v[128:129], v[128:129], v[130:131]
	s_nop 0
	v_pk_mul_f32 v[66:67], v[66:67], v[128:129]
	v_add_u32_e32 v128, 0x80, v170
	v_ashrrev_i32_e32 v129, 31, v128
	v_lshlrev_b64 v[128:129], 13, v[128:129]
	v_lshl_add_u64 v[128:129], s[50:51], 0, v[128:129]
	v_lshl_add_u64 v[128:129], v[128:129], 0, v[172:173]
	v_add_co_u32_e32 v132, vcc, s81, v128
	v_lshl_add_u64 v[130:131], v[128:129], 0, s[72:73]
	s_nop 0
	v_addc_co_u32_e32 v133, vcc, 0, v129, vcc
	global_load_dwordx4 v[152:155], v[128:129], off nt
	global_load_dwordx4 v[156:159], v[132:133], off nt
	global_load_dwordx4 v[144:147], v[128:129], off offset:256 nt
	global_load_dwordx4 v[148:151], v[130:131], off offset:256 nt
	v_add_u32_e32 v128, 0x90, v170
	v_ashrrev_i32_e32 v129, 31, v128
	v_lshlrev_b64 v[128:129], 13, v[128:129]
	v_lshl_add_u64 v[128:129], s[50:51], 0, v[128:129]
	v_lshl_add_u64 v[128:129], v[128:129], 0, v[172:173]
	v_add_co_u32_e32 v130, vcc, s81, v128
	v_lshl_add_u64 v[132:133], v[128:129], 0, s[72:73]
	s_nop 0
	v_addc_co_u32_e32 v131, vcc, 0, v129, vcc
	global_load_dwordx4 v[136:139], v[128:129], off nt
	global_load_dwordx4 v[140:143], v[130:131], off nt
	s_nop 0
	global_load_dwordx4 v[128:131], v[128:129], off offset:256 nt
	s_nop 0
	global_load_dwordx4 v[132:135], v[132:133], off offset:256 nt
	s_waitcnt vmcnt(0)
	s_nop 0
	v_lshlrev_b32_e32 v167, 16, v156
	v_and_b32_e32 v156, 0xffff0000, v156
	v_lshlrev_b32_e32 v180, 16, v152
	v_and_b32_e32 v181, 0xffff0000, v152
	v_lshlrev_b32_e32 v152, 16, v157
	v_rcp_f32_e32 v179, v156
	v_rcp_f32_e32 v156, v152
	v_and_b32_e32 v152, 0xffff0000, v157
	v_rcp_f32_e32 v157, v152
	v_lshlrev_b32_e32 v152, 16, v153
	v_and_b32_e32 v153, 0xffff0000, v153
	v_rcp_f32_e32 v178, v167
	v_pk_mul_f32 v[152:153], v[156:157], v[152:153]
	v_lshlrev_b32_e32 v156, 16, v154
	v_pk_mul_f32 v[62:63], v[62:63], v[152:153]
	v_lshlrev_b32_e32 v152, 16, v158
	v_and_b32_e32 v153, 0xffff0000, v158
	v_rcp_f32_e32 v152, v152
	v_rcp_f32_e32 v153, v153
	v_and_b32_e32 v157, 0xffff0000, v154
	v_lshlrev_b32_e32 v154, 16, v155
	v_and_b32_e32 v155, 0xffff0000, v155
	v_pk_mul_f32 v[152:153], v[152:153], v[156:157]
	v_pk_mul_f32 v[178:179], v[178:179], v[180:181]
	v_pk_mul_f32 v[56:57], v[56:57], v[152:153]
	v_lshlrev_b32_e32 v152, 16, v159
	v_and_b32_e32 v153, 0xffff0000, v159
	v_rcp_f32_e32 v152, v152
	v_rcp_f32_e32 v153, v153
	v_pk_mul_f32 v[60:61], v[60:61], v[178:179]
	v_pk_mul_f32 v[152:153], v[152:153], v[154:155]
	s_nop 0
	v_pk_mul_f32 v[58:59], v[58:59], v[152:153]
	v_lshlrev_b32_e32 v152, 16, v148
	v_and_b32_e32 v148, 0xffff0000, v148
	v_lshlrev_b32_e32 v154, 16, v144
	v_and_b32_e32 v155, 0xffff0000, v144
	v_lshlrev_b32_e32 v144, 16, v149
	v_rcp_f32_e32 v153, v148
	v_rcp_f32_e32 v148, v144
	v_and_b32_e32 v144, 0xffff0000, v149
	v_rcp_f32_e32 v149, v144
	v_lshlrev_b32_e32 v144, 16, v145
	v_and_b32_e32 v145, 0xffff0000, v145
	v_rcp_f32_e32 v152, v152
	v_pk_mul_f32 v[144:145], v[148:149], v[144:145]
	v_lshlrev_b32_e32 v148, 16, v146
	v_pk_mul_f32 v[54:55], v[54:55], v[144:145]
	v_lshlrev_b32_e32 v144, 16, v150
	v_and_b32_e32 v145, 0xffff0000, v150
	v_rcp_f32_e32 v144, v144
	v_rcp_f32_e32 v145, v145
	v_and_b32_e32 v149, 0xffff0000, v146
	v_lshlrev_b32_e32 v146, 16, v147
	v_and_b32_e32 v147, 0xffff0000, v147
	v_pk_mul_f32 v[144:145], v[144:145], v[148:149]
	v_pk_mul_f32 v[152:153], v[152:153], v[154:155]
	v_pk_mul_f32 v[44:45], v[44:45], v[144:145]
	v_lshlrev_b32_e32 v144, 16, v151
	v_and_b32_e32 v145, 0xffff0000, v151
	v_rcp_f32_e32 v144, v144
	v_rcp_f32_e32 v145, v145
	v_pk_mul_f32 v[52:53], v[52:53], v[152:153]
	v_pk_mul_f32 v[144:145], v[144:145], v[146:147]
	s_nop 0
	v_pk_mul_f32 v[46:47], v[46:47], v[144:145]
	v_lshlrev_b32_e32 v144, 16, v140
	v_and_b32_e32 v140, 0xffff0000, v140
	v_lshlrev_b32_e32 v146, 16, v136
	v_and_b32_e32 v147, 0xffff0000, v136
	v_lshlrev_b32_e32 v136, 16, v141
	v_rcp_f32_e32 v145, v140
	v_rcp_f32_e32 v140, v136
	v_and_b32_e32 v136, 0xffff0000, v141
	v_rcp_f32_e32 v141, v136
	v_lshlrev_b32_e32 v136, 16, v137
	v_and_b32_e32 v137, 0xffff0000, v137
	v_rcp_f32_e32 v144, v144
	v_pk_mul_f32 v[136:137], v[140:141], v[136:137]
	v_lshlrev_b32_e32 v140, 16, v138
	v_pk_mul_f32 v[50:51], v[50:51], v[136:137]
	v_lshlrev_b32_e32 v136, 16, v142
	v_and_b32_e32 v137, 0xffff0000, v142
	v_rcp_f32_e32 v136, v136
	v_rcp_f32_e32 v137, v137
	v_and_b32_e32 v141, 0xffff0000, v138
	v_lshlrev_b32_e32 v138, 16, v139
	v_and_b32_e32 v139, 0xffff0000, v139
	v_pk_mul_f32 v[136:137], v[136:137], v[140:141]
	v_pk_mul_f32 v[144:145], v[144:145], v[146:147]
	v_pk_mul_f32 v[40:41], v[40:41], v[136:137]
	v_lshlrev_b32_e32 v136, 16, v143
	v_and_b32_e32 v137, 0xffff0000, v143
	v_rcp_f32_e32 v136, v136
	v_rcp_f32_e32 v137, v137
	v_pk_mul_f32 v[48:49], v[48:49], v[144:145]
	v_pk_mul_f32 v[136:137], v[136:137], v[138:139]
	s_nop 0
	v_pk_mul_f32 v[42:43], v[42:43], v[136:137]
	v_lshlrev_b32_e32 v136, 16, v132
	v_and_b32_e32 v132, 0xffff0000, v132
	v_lshlrev_b32_e32 v138, 16, v128
	v_and_b32_e32 v139, 0xffff0000, v128
	v_lshlrev_b32_e32 v128, 16, v133
	v_rcp_f32_e32 v137, v132
	v_rcp_f32_e32 v132, v128
	v_and_b32_e32 v128, 0xffff0000, v133
	v_rcp_f32_e32 v133, v128
	v_lshlrev_b32_e32 v128, 16, v129
	v_and_b32_e32 v129, 0xffff0000, v129
	v_rcp_f32_e32 v136, v136
	v_pk_mul_f32 v[128:129], v[132:133], v[128:129]
	v_lshlrev_b32_e32 v132, 16, v130
	v_pk_mul_f32 v[38:39], v[38:39], v[128:129]
	v_lshlrev_b32_e32 v128, 16, v134
	v_and_b32_e32 v129, 0xffff0000, v134
	v_rcp_f32_e32 v128, v128
	v_rcp_f32_e32 v129, v129
	v_and_b32_e32 v133, 0xffff0000, v130
	v_lshlrev_b32_e32 v130, 16, v131
	v_and_b32_e32 v131, 0xffff0000, v131
	v_pk_mul_f32 v[128:129], v[128:129], v[132:133]
	v_pk_mul_f32 v[136:137], v[136:137], v[138:139]
	v_pk_mul_f32 v[28:29], v[28:29], v[128:129]
	v_lshlrev_b32_e32 v128, 16, v135
	v_and_b32_e32 v129, 0xffff0000, v135
	v_rcp_f32_e32 v128, v128
	v_rcp_f32_e32 v129, v129
	v_pk_mul_f32 v[36:37], v[36:37], v[136:137]
	v_pk_mul_f32 v[128:129], v[128:129], v[130:131]
	s_nop 0
	v_pk_mul_f32 v[30:31], v[30:31], v[128:129]
	v_add_u32_e32 v128, 0xa0, v170
	v_ashrrev_i32_e32 v129, 31, v128
	v_lshlrev_b64 v[128:129], 13, v[128:129]
	v_lshl_add_u64 v[128:129], s[50:51], 0, v[128:129]
	v_lshl_add_u64 v[128:129], v[128:129], 0, v[172:173]
	v_add_co_u32_e32 v132, vcc, s81, v128
	v_lshl_add_u64 v[130:131], v[128:129], 0, s[72:73]
	s_nop 0
	v_addc_co_u32_e32 v133, vcc, 0, v129, vcc
	global_load_dwordx4 v[152:155], v[128:129], off nt
	global_load_dwordx4 v[156:159], v[132:133], off nt
	global_load_dwordx4 v[144:147], v[128:129], off offset:256 nt
	global_load_dwordx4 v[148:151], v[130:131], off offset:256 nt
	v_add_u32_e32 v128, 0xb0, v170
	v_ashrrev_i32_e32 v129, 31, v128
	v_lshlrev_b64 v[128:129], 13, v[128:129]
	v_lshl_add_u64 v[128:129], s[50:51], 0, v[128:129]
	v_lshl_add_u64 v[128:129], v[128:129], 0, v[172:173]
	v_add_co_u32_e32 v130, vcc, s81, v128
	v_lshl_add_u64 v[132:133], v[128:129], 0, s[72:73]
	s_nop 0
	v_addc_co_u32_e32 v131, vcc, 0, v129, vcc
	global_load_dwordx4 v[136:139], v[128:129], off nt
	global_load_dwordx4 v[140:143], v[130:131], off nt
	s_nop 0
	global_load_dwordx4 v[128:131], v[128:129], off offset:256 nt
	s_nop 0
	global_load_dwordx4 v[132:135], v[132:133], off offset:256 nt
	s_waitcnt vmcnt(0)
	s_nop 0
	v_lshlrev_b32_e32 v167, 16, v156
	v_and_b32_e32 v156, 0xffff0000, v156
	v_lshlrev_b32_e32 v172, 16, v152
	v_and_b32_e32 v173, 0xffff0000, v152
	v_lshlrev_b32_e32 v152, 16, v157
	v_rcp_f32_e32 v171, v156
	v_rcp_f32_e32 v156, v152
	v_and_b32_e32 v152, 0xffff0000, v157
	v_rcp_f32_e32 v157, v152
	v_lshlrev_b32_e32 v152, 16, v153
	v_and_b32_e32 v153, 0xffff0000, v153
	v_rcp_f32_e32 v170, v167
	v_pk_mul_f32 v[152:153], v[156:157], v[152:153]
	v_lshlrev_b32_e32 v156, 16, v154
	v_pk_mul_f32 v[34:35], v[34:35], v[152:153]
	v_lshlrev_b32_e32 v152, 16, v158
	v_and_b32_e32 v153, 0xffff0000, v158
	v_rcp_f32_e32 v152, v152
	v_rcp_f32_e32 v153, v153
	v_and_b32_e32 v157, 0xffff0000, v154
	v_lshlrev_b32_e32 v154, 16, v155
	v_and_b32_e32 v155, 0xffff0000, v155
	v_pk_mul_f32 v[152:153], v[152:153], v[156:157]
	v_pk_mul_f32 v[170:171], v[170:171], v[172:173]
	v_pk_mul_f32 v[24:25], v[24:25], v[152:153]
	v_lshlrev_b32_e32 v152, 16, v159
	v_and_b32_e32 v153, 0xffff0000, v159
	v_rcp_f32_e32 v152, v152
	v_rcp_f32_e32 v153, v153
	v_pk_mul_f32 v[32:33], v[32:33], v[170:171]
	v_pk_mul_f32 v[152:153], v[152:153], v[154:155]
	s_nop 0
	v_pk_mul_f32 v[26:27], v[26:27], v[152:153]
	v_lshlrev_b32_e32 v152, 16, v148
	v_and_b32_e32 v148, 0xffff0000, v148
	v_lshlrev_b32_e32 v154, 16, v144
	v_and_b32_e32 v155, 0xffff0000, v144
	v_lshlrev_b32_e32 v144, 16, v149
	v_rcp_f32_e32 v153, v148
	v_rcp_f32_e32 v148, v144
	v_and_b32_e32 v144, 0xffff0000, v149
	v_rcp_f32_e32 v149, v144
	v_lshlrev_b32_e32 v144, 16, v145
	v_and_b32_e32 v145, 0xffff0000, v145
	v_rcp_f32_e32 v152, v152
	v_pk_mul_f32 v[144:145], v[148:149], v[144:145]
	v_lshlrev_b32_e32 v148, 16, v146
	v_pk_mul_f32 v[22:23], v[22:23], v[144:145]
	v_lshlrev_b32_e32 v144, 16, v150
	v_and_b32_e32 v145, 0xffff0000, v150
	v_rcp_f32_e32 v144, v144
	v_rcp_f32_e32 v145, v145
	v_and_b32_e32 v149, 0xffff0000, v146
	v_lshlrev_b32_e32 v146, 16, v147
	v_and_b32_e32 v147, 0xffff0000, v147
	v_pk_mul_f32 v[144:145], v[144:145], v[148:149]
	v_pk_mul_f32 v[152:153], v[152:153], v[154:155]
	v_pk_mul_f32 v[12:13], v[12:13], v[144:145]
	v_lshlrev_b32_e32 v144, 16, v151
	v_and_b32_e32 v145, 0xffff0000, v151
	v_rcp_f32_e32 v144, v144
	v_rcp_f32_e32 v145, v145
	v_pk_mul_f32 v[20:21], v[20:21], v[152:153]
	v_pk_mul_f32 v[144:145], v[144:145], v[146:147]
	s_nop 0
	v_pk_mul_f32 v[14:15], v[14:15], v[144:145]
	v_lshlrev_b32_e32 v144, 16, v140
	v_and_b32_e32 v140, 0xffff0000, v140
	v_lshlrev_b32_e32 v146, 16, v136
	v_and_b32_e32 v147, 0xffff0000, v136
	v_lshlrev_b32_e32 v136, 16, v141
	v_rcp_f32_e32 v145, v140
	v_rcp_f32_e32 v140, v136
	v_and_b32_e32 v136, 0xffff0000, v141
	v_rcp_f32_e32 v141, v136
	v_lshlrev_b32_e32 v136, 16, v137
	v_and_b32_e32 v137, 0xffff0000, v137
	v_rcp_f32_e32 v144, v144
	v_pk_mul_f32 v[136:137], v[140:141], v[136:137]
	v_lshlrev_b32_e32 v140, 16, v138
	v_pk_mul_f32 v[18:19], v[18:19], v[136:137]
	v_lshlrev_b32_e32 v136, 16, v142
	v_and_b32_e32 v137, 0xffff0000, v142
	v_rcp_f32_e32 v136, v136
	v_rcp_f32_e32 v137, v137
	v_and_b32_e32 v141, 0xffff0000, v138
	v_lshlrev_b32_e32 v138, 16, v139
	v_and_b32_e32 v139, 0xffff0000, v139
	v_pk_mul_f32 v[136:137], v[136:137], v[140:141]
	v_pk_mul_f32 v[144:145], v[144:145], v[146:147]
	v_pk_mul_f32 v[8:9], v[8:9], v[136:137]
	v_lshlrev_b32_e32 v136, 16, v143
	v_and_b32_e32 v137, 0xffff0000, v143
	v_rcp_f32_e32 v136, v136
	v_rcp_f32_e32 v137, v137
	v_pk_mul_f32 v[16:17], v[16:17], v[144:145]
	v_pk_mul_f32 v[136:137], v[136:137], v[138:139]
	s_nop 0
	v_pk_mul_f32 v[10:11], v[10:11], v[136:137]
	v_lshlrev_b32_e32 v136, 16, v132
	v_and_b32_e32 v132, 0xffff0000, v132
	v_lshlrev_b32_e32 v138, 16, v128
	v_and_b32_e32 v139, 0xffff0000, v128
	v_lshlrev_b32_e32 v128, 16, v133
	v_rcp_f32_e32 v137, v132
	v_rcp_f32_e32 v132, v128
	v_and_b32_e32 v128, 0xffff0000, v133
	v_rcp_f32_e32 v133, v128
	v_lshlrev_b32_e32 v128, 16, v129
	v_and_b32_e32 v129, 0xffff0000, v129
	v_rcp_f32_e32 v136, v136
	v_pk_mul_f32 v[128:129], v[132:133], v[128:129]
	v_lshlrev_b32_e32 v132, 16, v130
	v_pk_mul_f32 v[6:7], v[6:7], v[128:129]
	v_lshlrev_b32_e32 v128, 16, v134
	v_and_b32_e32 v129, 0xffff0000, v134
	v_rcp_f32_e32 v128, v128
	v_rcp_f32_e32 v129, v129
	v_and_b32_e32 v133, 0xffff0000, v130
	v_lshlrev_b32_e32 v130, 16, v131
	v_and_b32_e32 v131, 0xffff0000, v131
	v_pk_mul_f32 v[128:129], v[128:129], v[132:133]
	v_pk_mul_f32 v[136:137], v[136:137], v[138:139]
	v_pk_mul_f32 v[0:1], v[0:1], v[128:129]
	v_lshlrev_b32_e32 v128, 16, v135
	v_and_b32_e32 v129, 0xffff0000, v135
	v_rcp_f32_e32 v128, v128
	v_rcp_f32_e32 v129, v129
	v_pk_mul_f32 v[4:5], v[4:5], v[136:137]
	v_pk_mul_f32 v[128:129], v[128:129], v[130:131]
	s_nop 0
	v_pk_mul_f32 v[2:3], v[2:3], v[128:129]
	s_branch .LBB0_888

.LBB0_974:
	s_add_u32 s2, vcc_lo, 0xfff80080
	s_addc_u32 s3, vcc_hi, -1
	s_add_i32 s87, 0, 0x10000
	v_add_u32_e32 v76, s87, v247
	ds_read_b128 v[64:67], v76
	ds_read_b128 v[68:71], v76 offset:1024
	ds_read_b128 v[72:75], v76 offset:2048
	ds_read_b128 v[76:79], v76 offset:3072
	s_cmp_eq_u32 s63, 28
	s_cselect_b32 s21, s18, s3
	s_cselect_b32 s20, s19, s2
	s_cselect_b32 s3, s34, s61
	s_cselect_b32 s2, s35, s45
	v_lshl_add_u64 v[176:177], vcc, 0, v[208:209]
	s_add_i32 m0, s16, 0xc000
	ds_read_b128 v[80:83], v249
	ds_read_b128 v[84:87], v249 offset:1024
	ds_read_b128 v[88:91], v249 offset:2048
	ds_read_b128 v[92:95], v249 offset:3072
	ds_read_b128 v[160:163], v249 offset:4096
	ds_read_b128 v[164:167], v249 offset:5120
	ds_read_b128 v[168:171], v249 offset:6144
	ds_read_b128 v[172:175], v249 offset:7168
	global_load_lds_dwordx4 v[176:177], off
	v_lshl_add_u64 v[176:177], vcc, 0, v[210:211]
	s_add_i32 m0, s16, 0xe000
	s_nop 0
	global_load_lds_dwordx4 v[176:177], off
	s_waitcnt lgkmcnt(8)
	s_barrier
	s_waitcnt lgkmcnt(0)
	s_setprio 1
	s_waitcnt lgkmcnt(0)
	v_mfma_f32_16x16x32_bf16 v[156:159], v[64:67], v[80:83], v[156:159]
	v_mfma_f32_16x16x32_bf16 v[152:155], v[72:75], v[80:83], v[152:155]
	v_mfma_f32_16x16x32_bf16 v[140:143], v[64:67], v[88:91], v[140:143]
	v_mfma_f32_16x16x32_bf16 v[136:139], v[72:75], v[88:91], v[136:139]
	v_mfma_f32_16x16x32_bf16 v[124:127], v[64:67], v[160:163], v[124:127]
	v_mfma_f32_16x16x32_bf16 v[120:123], v[72:75], v[160:163], v[120:123]
	v_mfma_f32_16x16x32_bf16 v[108:111], v[64:67], v[168:171], v[108:111]
	v_mfma_f32_16x16x32_bf16 v[104:107], v[72:75], v[168:171], v[104:107]
	v_mfma_f32_16x16x32_bf16 v[156:159], v[68:71], v[84:87], v[156:159]
	v_mfma_f32_16x16x32_bf16 v[152:155], v[76:79], v[84:87], v[152:155]
	v_mfma_f32_16x16x32_bf16 v[140:143], v[68:71], v[92:95], v[140:143]
	v_mfma_f32_16x16x32_bf16 v[136:139], v[76:79], v[92:95], v[136:139]
	v_mfma_f32_16x16x32_bf16 v[124:127], v[68:71], v[164:167], v[124:127]
	v_mfma_f32_16x16x32_bf16 v[120:123], v[76:79], v[164:167], v[120:123]
	v_mfma_f32_16x16x32_bf16 v[108:111], v[68:71], v[172:175], v[108:111]
	v_mfma_f32_16x16x32_bf16 v[104:107], v[76:79], v[172:175], v[104:107]
	s_setprio 0
	s_barrier
	s_add_i32 s90, 0, 0x14000
	s_add_i32 s87, s87, s11
	v_add_u32_e32 v188, s90, v247
	v_lshl_add_u64 v[220:221], s[2:3], 0, v[194:195]
	s_mov_b32 m0, s87
	ds_read_b128 v[176:179], v188
	ds_read_b128 v[180:183], v188 offset:1024
	ds_read_b128 v[184:187], v188 offset:2048
	ds_read_b128 v[188:191], v188 offset:3072
	global_load_lds_dwordx4 v[220:221], off
	v_lshl_add_u64 v[222:223], s[2:3], 0, v[206:207]
	s_add_i32 m0, s87, 0x2000
	s_nop 0
	global_load_lds_dwordx4 v[222:223], off
	s_barrier
	s_waitcnt lgkmcnt(0)
	s_setprio 1
	s_waitcnt lgkmcnt(0)
	v_mfma_f32_16x16x32_bf16 v[148:151], v[176:179], v[80:83], v[148:151]
	v_mfma_f32_16x16x32_bf16 v[80:83], v[184:187], v[80:83], v[144:147]
	v_mfma_f32_16x16x32_bf16 v[148:151], v[180:183], v[84:87], v[148:151]
	v_mfma_f32_16x16x32_bf16 v[80:83], v[188:191], v[84:87], v[80:83]
	v_mfma_f32_16x16x32_bf16 v[84:87], v[176:179], v[88:91], v[132:135]
	v_mfma_f32_16x16x32_bf16 v[88:91], v[184:187], v[88:91], v[128:131]
	v_mfma_f32_16x16x32_bf16 v[112:115], v[184:187], v[160:163], v[112:115]
	v_mfma_f32_16x16x32_bf16 v[100:103], v[176:179], v[168:171], v[100:103]
	v_mfma_f32_16x16x32_bf16 v[96:99], v[184:187], v[168:171], v[96:99]
	v_mfma_f32_16x16x32_bf16 v[84:87], v[180:183], v[92:95], v[84:87]
	v_mfma_f32_16x16x32_bf16 v[88:91], v[188:191], v[92:95], v[88:91]
	v_mfma_f32_16x16x32_bf16 v[92:95], v[176:179], v[160:163], v[116:119]
	v_mfma_f32_16x16x32_bf16 v[112:115], v[188:191], v[164:167], v[112:115]
	v_mfma_f32_16x16x32_bf16 v[100:103], v[180:183], v[172:175], v[100:103]
	v_mfma_f32_16x16x32_bf16 v[96:99], v[188:191], v[172:175], v[96:99]
	v_mfma_f32_16x16x32_bf16 v[92:95], v[180:183], v[164:167], v[92:95]
	s_setprio 0
	s_mov_b32 m0, s16
	v_lshl_add_u64 v[224:225], s[20:21], 0, v[202:203]
	s_barrier
	ds_read_b128 v[116:119], v249 offset:16384
	ds_read_b128 v[128:131], v249 offset:17408
	ds_read_b128 v[132:135], v249 offset:18432
	ds_read_b128 v[144:147], v249 offset:19456
	ds_read_b128 v[160:163], v249 offset:20480
	ds_read_b128 v[164:167], v249 offset:21504
	ds_read_b128 v[168:171], v249 offset:22528
	ds_read_b128 v[172:175], v249 offset:23552
	global_load_lds_dwordx4 v[224:225], off
	v_lshl_add_u64 v[226:227], s[20:21], 0, v[204:205]
	s_mov_b32 m0, s53
	s_nop 0
	global_load_lds_dwordx4 v[226:227], off
	s_barrier
	s_waitcnt lgkmcnt(0)
	s_setprio 1
	s_waitcnt lgkmcnt(0)
	v_mfma_f32_16x16x32_bf16 v[60:63], v[64:67], v[116:119], v[60:63]
	v_mfma_f32_16x16x32_bf16 v[56:59], v[72:75], v[116:119], v[56:59]
	v_mfma_f32_16x16x32_bf16 v[44:47], v[64:67], v[132:135], v[44:47]
	v_mfma_f32_16x16x32_bf16 v[40:43], v[72:75], v[132:135], v[40:43]
	v_mfma_f32_16x16x32_bf16 v[28:31], v[64:67], v[160:163], v[28:31]
	v_mfma_f32_16x16x32_bf16 v[24:27], v[72:75], v[160:163], v[24:27]
	v_mfma_f32_16x16x32_bf16 v[12:15], v[64:67], v[168:171], v[12:15]
	v_mfma_f32_16x16x32_bf16 v[8:11], v[72:75], v[168:171], v[8:11]
	v_mfma_f32_16x16x32_bf16 v[60:63], v[68:71], v[128:131], v[60:63]
	v_mfma_f32_16x16x32_bf16 v[56:59], v[76:79], v[128:131], v[56:59]
	v_mfma_f32_16x16x32_bf16 v[44:47], v[68:71], v[144:147], v[44:47]
	v_mfma_f32_16x16x32_bf16 v[40:43], v[76:79], v[144:147], v[40:43]
	v_mfma_f32_16x16x32_bf16 v[28:31], v[68:71], v[164:167], v[28:31]
	v_mfma_f32_16x16x32_bf16 v[24:27], v[76:79], v[164:167], v[24:27]
	v_mfma_f32_16x16x32_bf16 v[12:15], v[68:71], v[172:175], v[12:15]
	v_mfma_f32_16x16x32_bf16 v[8:11], v[76:79], v[172:175], v[8:11]
	s_setprio 0
	s_barrier
	s_add_u32 s88, s2, 0x80000
	s_addc_u32 s89, s3, 0
	s_add_i32 s87, s90, s11
	v_lshl_add_u64 v[64:65], s[88:89], 0, v[194:195]
	s_mov_b32 m0, s87
	s_nop 0
	global_load_lds_dwordx4 v[64:65], off
	v_lshl_add_u64 v[64:65], s[88:89], 0, v[206:207]
	s_add_i32 m0, s87, 0x2000
	s_nop 0
	global_load_lds_dwordx4 v[64:65], off
	s_waitcnt vmcnt(6)
	s_barrier
	s_setprio 1
	v_mfma_f32_16x16x32_bf16 v[52:55], v[176:179], v[116:119], v[52:55]
	v_mfma_f32_16x16x32_bf16 v[48:51], v[184:187], v[116:119], v[48:51]
	v_mfma_f32_16x16x32_bf16 v[36:39], v[176:179], v[132:135], v[36:39]
	v_mfma_f32_16x16x32_bf16 v[32:35], v[184:187], v[132:135], v[32:35]
	v_mfma_f32_16x16x32_bf16 v[20:23], v[176:179], v[160:163], v[20:23]
	v_mfma_f32_16x16x32_bf16 v[16:19], v[184:187], v[160:163], v[16:19]
	v_mfma_f32_16x16x32_bf16 v[4:7], v[176:179], v[168:171], v[4:7]
	v_mfma_f32_16x16x32_bf16 v[0:3], v[184:187], v[168:171], v[0:3]
	v_mfma_f32_16x16x32_bf16 v[52:55], v[180:183], v[128:131], v[52:55]
	v_mfma_f32_16x16x32_bf16 v[48:51], v[188:191], v[128:131], v[48:51]
	v_mfma_f32_16x16x32_bf16 v[36:39], v[180:183], v[144:147], v[36:39]
	v_mfma_f32_16x16x32_bf16 v[32:35], v[188:191], v[144:147], v[32:35]
	v_mfma_f32_16x16x32_bf16 v[20:23], v[180:183], v[164:167], v[20:23]
	v_mfma_f32_16x16x32_bf16 v[16:19], v[188:191], v[164:167], v[16:19]
	v_mfma_f32_16x16x32_bf16 v[4:7], v[180:183], v[172:175], v[4:7]
	v_mfma_f32_16x16x32_bf16 v[0:3], v[188:191], v[172:175], v[0:3]
	s_setprio 0
	s_add_i32 s87, 0, 0x18000
	v_add_u32_e32 v76, s87, v247
	s_barrier
	ds_read_b128 v[64:67], v76
	ds_read_b128 v[68:71], v76 offset:1024
	ds_read_b128 v[72:75], v76 offset:2048
	ds_read_b128 v[76:79], v76 offset:3072
	s_add_u32 s20, s20, 0x80000
	s_addc_u32 s21, s21, 0
	s_mov_b32 m0, s68
	v_lshl_add_u64 v[132:133], s[20:21], 0, v[202:203]
	ds_read_b128 v[116:119], v249 offset:32768
	ds_read_b128 v[128:131], v249 offset:33792
	ds_read_b128 v[160:163], v249 offset:34816
	ds_read_b128 v[164:167], v249 offset:35840
	ds_read_b128 v[168:171], v249 offset:36864
	ds_read_b128 v[172:175], v249 offset:37888
	ds_read_b128 v[176:179], v249 offset:38912
	ds_read_b128 v[180:183], v249 offset:39936
	global_load_lds_dwordx4 v[132:133], off
	v_lshl_add_u64 v[132:133], s[20:21], 0, v[204:205]
	s_mov_b32 m0, s69
	s_nop 0
	global_load_lds_dwordx4 v[132:133], off
	s_waitcnt lgkmcnt(8)
	s_barrier
	s_waitcnt lgkmcnt(0)
	s_setprio 1
	s_waitcnt lgkmcnt(0)
	v_mfma_f32_16x16x32_bf16 v[132:135], v[64:67], v[116:119], v[156:159]
	v_mfma_f32_16x16x32_bf16 v[156:159], v[68:71], v[128:131], v[132:135]
	v_mfma_f32_16x16x32_bf16 v[132:135], v[72:75], v[116:119], v[152:155]
	v_mfma_f32_16x16x32_bf16 v[152:155], v[76:79], v[128:131], v[132:135]
	v_mfma_f32_16x16x32_bf16 v[132:135], v[64:67], v[160:163], v[140:143]
	v_mfma_f32_16x16x32_bf16 v[140:143], v[68:71], v[164:167], v[132:135]
	v_mfma_f32_16x16x32_bf16 v[132:135], v[72:75], v[160:163], v[136:139]
	v_mfma_f32_16x16x32_bf16 v[124:127], v[64:67], v[168:171], v[124:127]
	v_mfma_f32_16x16x32_bf16 v[120:123], v[72:75], v[168:171], v[120:123]
	v_mfma_f32_16x16x32_bf16 v[108:111], v[64:67], v[176:179], v[108:111]
	v_mfma_f32_16x16x32_bf16 v[104:107], v[72:75], v[176:179], v[104:107]
	v_mfma_f32_16x16x32_bf16 v[136:139], v[76:79], v[164:167], v[132:135]
	v_mfma_f32_16x16x32_bf16 v[124:127], v[68:71], v[172:175], v[124:127]
	v_mfma_f32_16x16x32_bf16 v[120:123], v[76:79], v[172:175], v[120:123]
	v_mfma_f32_16x16x32_bf16 v[108:111], v[68:71], v[180:183], v[108:111]
	v_mfma_f32_16x16x32_bf16 v[104:107], v[76:79], v[180:183], v[104:107]
	s_setprio 0
	s_barrier
	s_add_i32 s20, 0, 0x1c000
	v_add_u32_e32 v132, s20, v247
	s_add_i32 s21, s87, s11
	ds_read_b128 v[184:187], v132
	ds_read_b128 v[188:191], v132 offset:1024
	ds_read_b128 v[212:215], v132 offset:2048
	ds_read_b128 v[216:219], v132 offset:3072
	v_lshl_add_u64 v[132:133], v[220:221], 0, s[26:27]
	s_mov_b32 m0, s21
	s_nop 0
	global_load_lds_dwordx4 v[132:133], off
	v_lshl_add_u64 v[132:133], v[222:223], 0, s[26:27]
	s_add_i32 m0, s21, 0x2000
	s_nop 0
	global_load_lds_dwordx4 v[132:133], off
	s_barrier
	s_waitcnt lgkmcnt(0)
	s_setprio 1
	s_waitcnt lgkmcnt(0)
	v_mfma_f32_16x16x32_bf16 v[80:83], v[212:215], v[116:119], v[80:83]
	v_mfma_f32_16x16x32_bf16 v[132:135], v[184:187], v[116:119], v[148:151]
	v_mfma_f32_16x16x32_bf16 v[144:147], v[216:219], v[128:131], v[80:83]
	v_mfma_f32_16x16x32_bf16 v[80:83], v[184:187], v[160:163], v[84:87]
	v_mfma_f32_16x16x32_bf16 v[148:151], v[188:191], v[128:131], v[132:135]
	v_mfma_f32_16x16x32_bf16 v[132:135], v[188:191], v[164:167], v[80:83]
	v_mfma_f32_16x16x32_bf16 v[80:83], v[212:215], v[160:163], v[88:91]
	v_mfma_f32_16x16x32_bf16 v[128:131], v[216:219], v[164:167], v[80:83]
	v_mfma_f32_16x16x32_bf16 v[80:83], v[184:187], v[168:171], v[92:95]
	v_mfma_f32_16x16x32_bf16 v[116:119], v[188:191], v[172:175], v[80:83]
	v_mfma_f32_16x16x32_bf16 v[80:83], v[212:215], v[168:171], v[112:115]
	v_mfma_f32_16x16x32_bf16 v[112:115], v[216:219], v[172:175], v[80:83]
	v_mfma_f32_16x16x32_bf16 v[80:83], v[184:187], v[176:179], v[100:103]
	v_mfma_f32_16x16x32_bf16 v[100:103], v[188:191], v[180:183], v[80:83]
	v_mfma_f32_16x16x32_bf16 v[80:83], v[212:215], v[176:179], v[96:99]
	v_mfma_f32_16x16x32_bf16 v[96:99], v[216:219], v[180:183], v[80:83]
	s_setprio 0
	s_mov_b32 m0, s71
	v_lshl_add_u64 v[176:177], v[224:225], 0, s[26:27]
	s_barrier
	s_nop 2
	ds_read_b128 v[80:83], v249 offset:49152
	ds_read_b128 v[84:87], v249 offset:50176
	ds_read_b128 v[88:91], v249 offset:51200
	ds_read_b128 v[92:95], v249 offset:52224
	ds_read_b128 v[160:163], v249 offset:53248
	ds_read_b128 v[164:167], v249 offset:54272
	ds_read_b128 v[168:171], v249 offset:55296
	ds_read_b128 v[172:175], v249 offset:56320
	global_load_lds_dwordx4 v[176:177], off
	v_lshl_add_u64 v[176:177], v[226:227], 0, s[26:27]
	s_mov_b32 m0, s74
	s_nop 0
	global_load_lds_dwordx4 v[176:177], off
	s_barrier
	s_waitcnt lgkmcnt(0)
	s_setprio 1
	s_waitcnt lgkmcnt(0)
	v_mfma_f32_16x16x32_bf16 v[60:63], v[64:67], v[80:83], v[60:63]
	v_mfma_f32_16x16x32_bf16 v[56:59], v[72:75], v[80:83], v[56:59]
	v_mfma_f32_16x16x32_bf16 v[44:47], v[64:67], v[88:91], v[44:47]
	v_mfma_f32_16x16x32_bf16 v[40:43], v[72:75], v[88:91], v[40:43]
	v_mfma_f32_16x16x32_bf16 v[28:31], v[64:67], v[160:163], v[28:31]
	v_mfma_f32_16x16x32_bf16 v[24:27], v[72:75], v[160:163], v[24:27]
	v_mfma_f32_16x16x32_bf16 v[12:15], v[64:67], v[168:171], v[12:15]
	v_mfma_f32_16x16x32_bf16 v[8:11], v[72:75], v[168:171], v[8:11]
	v_mfma_f32_16x16x32_bf16 v[60:63], v[68:71], v[84:87], v[60:63]
	v_mfma_f32_16x16x32_bf16 v[56:59], v[76:79], v[84:87], v[56:59]
	v_mfma_f32_16x16x32_bf16 v[44:47], v[68:71], v[92:95], v[44:47]
	v_mfma_f32_16x16x32_bf16 v[40:43], v[76:79], v[92:95], v[40:43]
	v_mfma_f32_16x16x32_bf16 v[28:31], v[68:71], v[164:167], v[28:31]
	v_mfma_f32_16x16x32_bf16 v[24:27], v[76:79], v[164:167], v[24:27]
	v_mfma_f32_16x16x32_bf16 v[12:15], v[68:71], v[172:175], v[12:15]
	v_mfma_f32_16x16x32_bf16 v[8:11], v[76:79], v[172:175], v[8:11]
	s_setprio 0
	s_barrier
	s_add_u32 s2, s2, 0x80080
	s_addc_u32 s3, s3, 0
	s_add_i32 s20, s20, s11
	v_lshl_add_u64 v[64:65], s[2:3], 0, v[194:195]
	s_mov_b32 m0, s20
	s_nop 0
	global_load_lds_dwordx4 v[64:65], off
	v_lshl_add_u64 v[64:65], s[2:3], 0, v[206:207]
	s_add_i32 m0, s20, 0x2000
	s_nop 0
	global_load_lds_dwordx4 v[64:65], off
	s_waitcnt vmcnt(6)
	s_barrier
	s_setprio 1
	v_mfma_f32_16x16x32_bf16 v[52:55], v[184:187], v[80:83], v[52:55]
	v_mfma_f32_16x16x32_bf16 v[48:51], v[212:215], v[80:83], v[48:51]
	v_mfma_f32_16x16x32_bf16 v[36:39], v[184:187], v[88:91], v[36:39]
	v_mfma_f32_16x16x32_bf16 v[32:35], v[212:215], v[88:91], v[32:35]
	v_mfma_f32_16x16x32_bf16 v[20:23], v[184:187], v[160:163], v[20:23]
	v_mfma_f32_16x16x32_bf16 v[16:19], v[212:215], v[160:163], v[16:19]
	v_mfma_f32_16x16x32_bf16 v[4:7], v[184:187], v[168:171], v[4:7]
	v_mfma_f32_16x16x32_bf16 v[0:3], v[212:215], v[168:171], v[0:3]
	v_mfma_f32_16x16x32_bf16 v[52:55], v[188:191], v[84:87], v[52:55]
	v_mfma_f32_16x16x32_bf16 v[48:51], v[216:219], v[84:87], v[48:51]
	v_mfma_f32_16x16x32_bf16 v[36:39], v[188:191], v[92:95], v[36:39]
	v_mfma_f32_16x16x32_bf16 v[32:35], v[216:219], v[92:95], v[32:35]
	v_mfma_f32_16x16x32_bf16 v[20:23], v[188:191], v[164:167], v[20:23]
	v_mfma_f32_16x16x32_bf16 v[16:19], v[216:219], v[164:167], v[16:19]
	v_mfma_f32_16x16x32_bf16 v[4:7], v[188:191], v[172:175], v[4:7]
	v_mfma_f32_16x16x32_bf16 v[0:3], v[216:219], v[172:175], v[0:3]
	s_setprio 0
	s_add_i32 s63, s63, 2
	s_add_u32 vcc_lo, vcc_lo, 0x100
	s_addc_u32 vcc_hi, vcc_hi, 0
	s_add_u32 s45, s45, 0x100
	s_addc_u32 s61, s61, 0
	s_cmp_gt_u32 s63, 29
	s_barrier
	s_cbranch_scc0 .LBB0_974
	v_lshl_or_b32 v212, s44, 8, v248
	v_cndmask_b32_e64 v64, 0, 1, s[30:31]
	v_lshl_add_u32 v214, s70, 8, v246
	v_ashrrev_i32_e32 v213, 31, v212
	v_mov_b32_e32 v216, 0
	v_mov_b32_e32 v67, 1.0
	v_cmp_ne_u32_e64 s[44:45], 1, v64
	s_andn2_b64 vcc, exec, s[30:31]
	v_mov_b32_e32 v66, 1.0
	v_mov_b32_e32 v65, 1.0
	v_mov_b32_e32 v64, 1.0
	v_mov_b32_e32 v75, 1.0
	v_mov_b32_e32 v74, 1.0
	v_mov_b32_e32 v73, 1.0
	v_mov_b32_e32 v72, 1.0
	v_mov_b32_e32 v83, 1.0
	v_mov_b32_e32 v82, 1.0
	v_mov_b32_e32 v81, 1.0
	v_mov_b32_e32 v80, 1.0
	v_mov_b32_e32 v91, 1.0
	v_mov_b32_e32 v90, 1.0
	v_mov_b32_e32 v89, 1.0
	v_mov_b32_e32 v88, 1.0
	v_mov_b32_e32 v71, 0
	v_mov_b32_e32 v70, 0
	v_mov_b32_e32 v69, 0
	v_mov_b32_e32 v68, 0
	v_mov_b32_e32 v79, 0
	v_mov_b32_e32 v78, 0
	v_mov_b32_e32 v77, 0
	v_mov_b32_e32 v76, 0
	v_mov_b32_e32 v87, 0
	v_mov_b32_e32 v86, 0
	v_mov_b32_e32 v85, 0
	v_mov_b32_e32 v84, 0
	v_mov_b32_e32 v95, 0
	v_mov_b32_e32 v94, 0
	v_mov_b32_e32 v93, 0
	v_mov_b32_e32 v92, 0
	s_cbranch_vccnz .LBB0_977
	v_lshlrev_b64 v[64:65], 2, v[212:213]
	v_lshl_add_u64 v[68:69], s[56:57], 0, v[64:65]
	v_lshl_add_u64 v[76:77], s[58:59], 0, v[64:65]
	global_load_dwordx4 v[80:83], v[68:69], off offset:16 nt
	global_load_dwordx4 v[88:91], v[68:69], off nt
	global_load_dwordx4 v[84:87], v[76:77], off offset:16 nt
	global_load_dwordx4 v[92:95], v[76:77], off nt
	global_load_dwordx4 v[64:67], v[68:69], off offset:528 nt
	global_load_dwordx4 v[72:75], v[68:69], off offset:512 nt
	s_nop 0
	global_load_dwordx4 v[68:71], v[76:77], off offset:528 nt
	s_nop 0
	global_load_dwordx4 v[76:79], v[76:77], off offset:512 nt
	s_waitcnt vmcnt(0)
.LBB0_977:
	v_ashrrev_i32_e32 v215, 31, v214
	v_add_u32_e32 v230, 16, v214
	v_lshl_add_u64 v[218:219], v[212:213], 1, s[48:49]
	v_lshlrev_b64 v[238:239], 12, v[214:215]
	v_ashrrev_i32_e32 v231, 31, v230
	v_add_u32_e32 v224, 32, v214
	v_lshl_add_u64 v[160:161], v[218:219], 0, v[238:239]
	v_lshlrev_b64 v[234:235], 12, v[230:231]
	v_ashrrev_i32_e32 v225, 31, v224
	v_add_u32_e32 v220, 48, v214
	global_load_dwordx4 v[188:191], v[160:161], off nt
	global_load_dwordx4 v[184:187], v[160:161], off offset:256 nt
	v_lshl_add_u64 v[160:161], v[218:219], 0, v[234:235]
	v_lshlrev_b64 v[228:229], 12, v[224:225]
	v_ashrrev_i32_e32 v221, 31, v220
	global_load_dwordx4 v[180:183], v[160:161], off nt
	global_load_dwordx4 v[176:179], v[160:161], off offset:256 nt
	v_lshl_add_u64 v[160:161], v[218:219], 0, v[228:229]
	v_lshlrev_b64 v[222:223], 12, v[220:221]
	global_load_dwordx4 v[172:175], v[160:161], off nt
	global_load_dwordx4 v[168:171], v[160:161], off offset:256 nt
	v_lshl_add_u64 v[160:161], v[218:219], 0, v[222:223]
	global_load_dwordx4 v[164:167], v[160:161], off nt
	s_nop 0
	global_load_dwordx4 v[160:163], v[160:161], off offset:256 nt
	s_and_b64 vcc, exec, s[44:45]
	v_mov_b32_e32 v217, 0
	v_mov_b32_e32 v226, 0
	v_mov_b32_e32 v227, 0
	v_mov_b32_e32 v232, 0
	v_mov_b32_e32 v233, 0
	v_mov_b32_e32 v236, 0
	v_mov_b32_e32 v237, 0
	s_cbranch_vccnz .LBB0_979
	v_lshl_add_u64 v[216:217], v[214:215], 3, s[50:51]
	v_lshl_add_u64 v[226:227], v[230:231], 3, s[50:51]
	v_lshl_add_u64 v[236:237], v[220:221], 3, s[50:51]
	v_lshl_add_u64 v[232:233], v[224:225], 3, s[50:51]
	global_load_dwordx2 v[250:251], v[236:237], off
	global_load_dwordx2 v[252:253], v[232:233], off
	s_nop 0
	global_load_dwordx2 v[226:227], v[226:227], off
	s_nop 0
	global_load_dwordx2 v[216:217], v[216:217], off
	s_waitcnt vmcnt(0)
	s_nop 0
	v_pk_mul_f32 v[236:237], v[216:217], s[28:29] op_sel_hi:[1,0]
	v_pk_mul_f32 v[232:233], v[226:227], s[28:29] op_sel_hi:[1,0]
	v_pk_mul_f32 v[226:227], v[252:253], s[28:29] op_sel_hi:[1,0]
	v_pk_mul_f32 v[216:217], v[250:251], s[28:29] op_sel_hi:[1,0]

.LBB0_1168:
	s_add_u32 s2, s42, 0xffe00080
	s_addc_u32 s3, s43, -1
	s_add_i32 s87, 0, 0x10000
	v_add_u32_e32 v76, s87, v235
	ds_read_b128 v[64:67], v76
	ds_read_b128 v[68:71], v76 offset:1024
	ds_read_b128 v[72:75], v76 offset:2048
	ds_read_b128 v[76:79], v76 offset:3072
	s_cmpk_eq_i32 s86, 0x7c
	s_cselect_b32 s21, s18, s3
	s_cselect_b32 s20, s19, s2
	s_cselect_b32 s3, s34, s61
	s_cselect_b32 s2, s35, s59
	v_lshl_add_u64 v[176:177], s[42:43], 0, v[204:205]
	s_add_i32 m0, s16, 0xc000
	ds_read_b128 v[80:83], v237
	ds_read_b128 v[84:87], v237 offset:1024
	ds_read_b128 v[88:91], v237 offset:2048
	ds_read_b128 v[92:95], v237 offset:3072
	ds_read_b128 v[160:163], v237 offset:4096
	ds_read_b128 v[164:167], v237 offset:5120
	ds_read_b128 v[168:171], v237 offset:6144
	ds_read_b128 v[172:175], v237 offset:7168
	global_load_lds_dwordx4 v[176:177], off
	v_lshl_add_u64 v[176:177], s[42:43], 0, v[206:207]
	s_add_i32 m0, s16, 0xe000
	s_nop 0
	global_load_lds_dwordx4 v[176:177], off
	s_waitcnt lgkmcnt(8)
	s_barrier
	s_waitcnt lgkmcnt(0)
	s_setprio 1
	s_waitcnt lgkmcnt(0)
	v_mfma_f32_16x16x32_bf16 v[156:159], v[64:67], v[80:83], v[156:159]
	v_mfma_f32_16x16x32_bf16 v[152:155], v[72:75], v[80:83], v[152:155]
	v_mfma_f32_16x16x32_bf16 v[140:143], v[64:67], v[88:91], v[140:143]
	v_mfma_f32_16x16x32_bf16 v[136:139], v[72:75], v[88:91], v[136:139]
	v_mfma_f32_16x16x32_bf16 v[124:127], v[64:67], v[160:163], v[124:127]
	v_mfma_f32_16x16x32_bf16 v[120:123], v[72:75], v[160:163], v[120:123]
	v_mfma_f32_16x16x32_bf16 v[108:111], v[64:67], v[168:171], v[108:111]
	v_mfma_f32_16x16x32_bf16 v[104:107], v[72:75], v[168:171], v[104:107]
	v_mfma_f32_16x16x32_bf16 v[156:159], v[68:71], v[84:87], v[156:159]
	v_mfma_f32_16x16x32_bf16 v[152:155], v[76:79], v[84:87], v[152:155]
	v_mfma_f32_16x16x32_bf16 v[140:143], v[68:71], v[92:95], v[140:143]
	v_mfma_f32_16x16x32_bf16 v[136:139], v[76:79], v[92:95], v[136:139]
	v_mfma_f32_16x16x32_bf16 v[124:127], v[68:71], v[164:167], v[124:127]
	v_mfma_f32_16x16x32_bf16 v[120:123], v[76:79], v[164:167], v[120:123]
	v_mfma_f32_16x16x32_bf16 v[108:111], v[68:71], v[172:175], v[108:111]
	v_mfma_f32_16x16x32_bf16 v[104:107], v[76:79], v[172:175], v[104:107]
	s_setprio 0
	s_barrier
	s_add_i32 s90, 0, 0x14000
	s_add_i32 s87, s87, s11
	v_add_u32_e32 v208, s90, v235
	v_lshl_add_u64 v[220:221], s[2:3], 0, v[194:195]
	s_mov_b32 m0, s87
	ds_read_b128 v[176:179], v208
	ds_read_b128 v[180:183], v208 offset:1024
	ds_read_b128 v[184:187], v208 offset:2048
	ds_read_b128 v[208:211], v208 offset:3072
	global_load_lds_dwordx4 v[220:221], off
	v_lshl_add_u64 v[222:223], s[2:3], 0, v[202:203]
	s_add_i32 m0, s87, 0x2000
	s_nop 0
	global_load_lds_dwordx4 v[222:223], off
	s_barrier
	s_waitcnt lgkmcnt(0)
	s_setprio 1
	s_waitcnt lgkmcnt(0)
	v_mfma_f32_16x16x32_bf16 v[148:151], v[176:179], v[80:83], v[148:151]
	v_mfma_f32_16x16x32_bf16 v[80:83], v[184:187], v[80:83], v[144:147]
	v_mfma_f32_16x16x32_bf16 v[148:151], v[180:183], v[84:87], v[148:151]
	v_mfma_f32_16x16x32_bf16 v[80:83], v[208:211], v[84:87], v[80:83]
	v_mfma_f32_16x16x32_bf16 v[84:87], v[176:179], v[88:91], v[132:135]
	v_mfma_f32_16x16x32_bf16 v[88:91], v[184:187], v[88:91], v[128:131]
	v_mfma_f32_16x16x32_bf16 v[112:115], v[184:187], v[160:163], v[112:115]
	v_mfma_f32_16x16x32_bf16 v[100:103], v[176:179], v[168:171], v[100:103]
	v_mfma_f32_16x16x32_bf16 v[96:99], v[184:187], v[168:171], v[96:99]
	v_mfma_f32_16x16x32_bf16 v[84:87], v[180:183], v[92:95], v[84:87]
	v_mfma_f32_16x16x32_bf16 v[88:91], v[208:211], v[92:95], v[88:91]
	v_mfma_f32_16x16x32_bf16 v[92:95], v[176:179], v[160:163], v[116:119]
	v_mfma_f32_16x16x32_bf16 v[112:115], v[208:211], v[164:167], v[112:115]
	v_mfma_f32_16x16x32_bf16 v[100:103], v[180:183], v[172:175], v[100:103]
	v_mfma_f32_16x16x32_bf16 v[96:99], v[208:211], v[172:175], v[96:99]
	v_mfma_f32_16x16x32_bf16 v[92:95], v[180:183], v[164:167], v[92:95]
	s_setprio 0
	s_mov_b32 m0, s16
	v_lshl_add_u64 v[224:225], s[20:21], 0, v[188:189]
	s_barrier
	ds_read_b128 v[116:119], v237 offset:16384
	ds_read_b128 v[128:131], v237 offset:17408
	ds_read_b128 v[132:135], v237 offset:18432
	ds_read_b128 v[144:147], v237 offset:19456
	ds_read_b128 v[160:163], v237 offset:20480
	ds_read_b128 v[164:167], v237 offset:21504
	ds_read_b128 v[168:171], v237 offset:22528
	ds_read_b128 v[172:175], v237 offset:23552
	global_load_lds_dwordx4 v[224:225], off
	v_lshl_add_u64 v[226:227], s[20:21], 0, v[190:191]
	s_mov_b32 m0, s53
	s_nop 0
	global_load_lds_dwordx4 v[226:227], off
	s_barrier
	s_waitcnt lgkmcnt(0)
	s_setprio 1
	s_waitcnt lgkmcnt(0)
	v_mfma_f32_16x16x32_bf16 v[60:63], v[64:67], v[116:119], v[60:63]
	v_mfma_f32_16x16x32_bf16 v[56:59], v[72:75], v[116:119], v[56:59]
	v_mfma_f32_16x16x32_bf16 v[44:47], v[64:67], v[132:135], v[44:47]
	v_mfma_f32_16x16x32_bf16 v[40:43], v[72:75], v[132:135], v[40:43]
	v_mfma_f32_16x16x32_bf16 v[28:31], v[64:67], v[160:163], v[28:31]
	v_mfma_f32_16x16x32_bf16 v[24:27], v[72:75], v[160:163], v[24:27]
	v_mfma_f32_16x16x32_bf16 v[12:15], v[64:67], v[168:171], v[12:15]
	v_mfma_f32_16x16x32_bf16 v[8:11], v[72:75], v[168:171], v[8:11]
	v_mfma_f32_16x16x32_bf16 v[60:63], v[68:71], v[128:131], v[60:63]
	v_mfma_f32_16x16x32_bf16 v[56:59], v[76:79], v[128:131], v[56:59]
	v_mfma_f32_16x16x32_bf16 v[44:47], v[68:71], v[144:147], v[44:47]
	v_mfma_f32_16x16x32_bf16 v[40:43], v[76:79], v[144:147], v[40:43]
	v_mfma_f32_16x16x32_bf16 v[28:31], v[68:71], v[164:167], v[28:31]
	v_mfma_f32_16x16x32_bf16 v[24:27], v[76:79], v[164:167], v[24:27]
	v_mfma_f32_16x16x32_bf16 v[12:15], v[68:71], v[172:175], v[12:15]
	v_mfma_f32_16x16x32_bf16 v[8:11], v[76:79], v[172:175], v[8:11]
	s_setprio 0
	s_barrier
	s_add_u32 s88, s2, 0x200000
	s_addc_u32 s89, s3, 0
	s_add_i32 s87, s90, s11
	v_lshl_add_u64 v[64:65], s[88:89], 0, v[194:195]
	s_mov_b32 m0, s87
	s_nop 0
	global_load_lds_dwordx4 v[64:65], off
	v_lshl_add_u64 v[64:65], s[88:89], 0, v[202:203]
	s_add_i32 m0, s87, 0x2000
	s_nop 0
	global_load_lds_dwordx4 v[64:65], off
	s_waitcnt vmcnt(6)
	s_barrier
	s_setprio 1
	v_mfma_f32_16x16x32_bf16 v[52:55], v[176:179], v[116:119], v[52:55]
	v_mfma_f32_16x16x32_bf16 v[48:51], v[184:187], v[116:119], v[48:51]
	v_mfma_f32_16x16x32_bf16 v[36:39], v[176:179], v[132:135], v[36:39]
	v_mfma_f32_16x16x32_bf16 v[32:35], v[184:187], v[132:135], v[32:35]
	v_mfma_f32_16x16x32_bf16 v[20:23], v[176:179], v[160:163], v[20:23]
	v_mfma_f32_16x16x32_bf16 v[16:19], v[184:187], v[160:163], v[16:19]
	v_mfma_f32_16x16x32_bf16 v[4:7], v[176:179], v[168:171], v[4:7]
	v_mfma_f32_16x16x32_bf16 v[0:3], v[184:187], v[168:171], v[0:3]
	v_mfma_f32_16x16x32_bf16 v[52:55], v[180:183], v[128:131], v[52:55]
	v_mfma_f32_16x16x32_bf16 v[48:51], v[208:211], v[128:131], v[48:51]
	v_mfma_f32_16x16x32_bf16 v[36:39], v[180:183], v[144:147], v[36:39]
	v_mfma_f32_16x16x32_bf16 v[32:35], v[208:211], v[144:147], v[32:35]
	v_mfma_f32_16x16x32_bf16 v[20:23], v[180:183], v[164:167], v[20:23]
	v_mfma_f32_16x16x32_bf16 v[16:19], v[208:211], v[164:167], v[16:19]
	v_mfma_f32_16x16x32_bf16 v[4:7], v[180:183], v[172:175], v[4:7]
	v_mfma_f32_16x16x32_bf16 v[0:3], v[208:211], v[172:175], v[0:3]
	s_setprio 0
	s_add_i32 s87, 0, 0x18000
	v_add_u32_e32 v76, s87, v235
	s_barrier
	ds_read_b128 v[64:67], v76
	ds_read_b128 v[68:71], v76 offset:1024
	ds_read_b128 v[72:75], v76 offset:2048
	ds_read_b128 v[76:79], v76 offset:3072
	s_add_u32 s20, s20, 0x200000
	s_addc_u32 s21, s21, 0
	s_mov_b32 m0, s67
	v_lshl_add_u64 v[132:133], s[20:21], 0, v[188:189]
	ds_read_b128 v[116:119], v237 offset:32768
	ds_read_b128 v[128:131], v237 offset:33792
	ds_read_b128 v[160:163], v237 offset:34816
	ds_read_b128 v[164:167], v237 offset:35840
	ds_read_b128 v[168:171], v237 offset:36864
	ds_read_b128 v[172:175], v237 offset:37888
	ds_read_b128 v[176:179], v237 offset:38912
	ds_read_b128 v[180:183], v237 offset:39936
	global_load_lds_dwordx4 v[132:133], off
	v_lshl_add_u64 v[132:133], s[20:21], 0, v[190:191]
	s_mov_b32 m0, s68
	s_nop 0
	global_load_lds_dwordx4 v[132:133], off
	s_waitcnt lgkmcnt(8)
	s_barrier
	s_waitcnt lgkmcnt(0)
	s_setprio 1
	s_waitcnt lgkmcnt(0)
	v_mfma_f32_16x16x32_bf16 v[132:135], v[64:67], v[116:119], v[156:159]
	v_mfma_f32_16x16x32_bf16 v[156:159], v[68:71], v[128:131], v[132:135]
	v_mfma_f32_16x16x32_bf16 v[132:135], v[72:75], v[116:119], v[152:155]
	v_mfma_f32_16x16x32_bf16 v[152:155], v[76:79], v[128:131], v[132:135]
	v_mfma_f32_16x16x32_bf16 v[132:135], v[64:67], v[160:163], v[140:143]
	v_mfma_f32_16x16x32_bf16 v[140:143], v[68:71], v[164:167], v[132:135]
	v_mfma_f32_16x16x32_bf16 v[132:135], v[72:75], v[160:163], v[136:139]
	v_mfma_f32_16x16x32_bf16 v[124:127], v[64:67], v[168:171], v[124:127]
	v_mfma_f32_16x16x32_bf16 v[120:123], v[72:75], v[168:171], v[120:123]
	v_mfma_f32_16x16x32_bf16 v[108:111], v[64:67], v[176:179], v[108:111]
	v_mfma_f32_16x16x32_bf16 v[104:107], v[72:75], v[176:179], v[104:107]
	v_mfma_f32_16x16x32_bf16 v[136:139], v[76:79], v[164:167], v[132:135]
	v_mfma_f32_16x16x32_bf16 v[124:127], v[68:71], v[172:175], v[124:127]
	v_mfma_f32_16x16x32_bf16 v[120:123], v[76:79], v[172:175], v[120:123]
	v_mfma_f32_16x16x32_bf16 v[108:111], v[68:71], v[180:183], v[108:111]
	v_mfma_f32_16x16x32_bf16 v[104:107], v[76:79], v[180:183], v[104:107]
	s_setprio 0
	s_barrier
	s_add_i32 s20, 0, 0x1c000
	v_add_u32_e32 v132, s20, v235
	s_add_i32 s21, s87, s11
	ds_read_b128 v[184:187], v132
	ds_read_b128 v[208:211], v132 offset:1024
	ds_read_b128 v[212:215], v132 offset:2048
	ds_read_b128 v[216:219], v132 offset:3072
	v_lshl_add_u64 v[132:133], v[220:221], 0, s[26:27]
	s_mov_b32 m0, s21
	s_nop 0
	global_load_lds_dwordx4 v[132:133], off
	v_lshl_add_u64 v[132:133], v[222:223], 0, s[26:27]
	s_add_i32 m0, s21, 0x2000
	s_nop 0
	global_load_lds_dwordx4 v[132:133], off
	s_barrier
	s_waitcnt lgkmcnt(0)
	s_setprio 1
	s_waitcnt lgkmcnt(0)
	v_mfma_f32_16x16x32_bf16 v[80:83], v[212:215], v[116:119], v[80:83]
	v_mfma_f32_16x16x32_bf16 v[132:135], v[184:187], v[116:119], v[148:151]
	v_mfma_f32_16x16x32_bf16 v[144:147], v[216:219], v[128:131], v[80:83]
	v_mfma_f32_16x16x32_bf16 v[80:83], v[184:187], v[160:163], v[84:87]
	v_mfma_f32_16x16x32_bf16 v[148:151], v[208:211], v[128:131], v[132:135]
	v_mfma_f32_16x16x32_bf16 v[132:135], v[208:211], v[164:167], v[80:83]
	v_mfma_f32_16x16x32_bf16 v[80:83], v[212:215], v[160:163], v[88:91]
	v_mfma_f32_16x16x32_bf16 v[128:131], v[216:219], v[164:167], v[80:83]
	v_mfma_f32_16x16x32_bf16 v[80:83], v[184:187], v[168:171], v[92:95]
	v_mfma_f32_16x16x32_bf16 v[116:119], v[208:211], v[172:175], v[80:83]
	v_mfma_f32_16x16x32_bf16 v[80:83], v[212:215], v[168:171], v[112:115]
	v_mfma_f32_16x16x32_bf16 v[112:115], v[216:219], v[172:175], v[80:83]
	v_mfma_f32_16x16x32_bf16 v[80:83], v[184:187], v[176:179], v[100:103]
	v_mfma_f32_16x16x32_bf16 v[100:103], v[208:211], v[180:183], v[80:83]
	v_mfma_f32_16x16x32_bf16 v[80:83], v[212:215], v[176:179], v[96:99]
	v_mfma_f32_16x16x32_bf16 v[96:99], v[216:219], v[180:183], v[80:83]
	s_setprio 0
	s_mov_b32 m0, s22
	v_lshl_add_u64 v[176:177], v[224:225], 0, s[26:27]
	s_barrier
	s_nop 2
	ds_read_b128 v[80:83], v237 offset:49152
	ds_read_b128 v[84:87], v237 offset:50176
	ds_read_b128 v[88:91], v237 offset:51200
	ds_read_b128 v[92:95], v237 offset:52224
	ds_read_b128 v[160:163], v237 offset:53248
	ds_read_b128 v[164:167], v237 offset:54272
	ds_read_b128 v[168:171], v237 offset:55296
	ds_read_b128 v[172:175], v237 offset:56320
	global_load_lds_dwordx4 v[176:177], off
	v_lshl_add_u64 v[176:177], v[226:227], 0, s[26:27]
	s_mov_b32 m0, s71
	s_nop 0
	global_load_lds_dwordx4 v[176:177], off
	s_barrier
	s_waitcnt lgkmcnt(0)
	s_setprio 1
	s_waitcnt lgkmcnt(0)
	v_mfma_f32_16x16x32_bf16 v[60:63], v[64:67], v[80:83], v[60:63]
	v_mfma_f32_16x16x32_bf16 v[56:59], v[72:75], v[80:83], v[56:59]
	v_mfma_f32_16x16x32_bf16 v[44:47], v[64:67], v[88:91], v[44:47]
	v_mfma_f32_16x16x32_bf16 v[40:43], v[72:75], v[88:91], v[40:43]
	v_mfma_f32_16x16x32_bf16 v[28:31], v[64:67], v[160:163], v[28:31]
	v_mfma_f32_16x16x32_bf16 v[24:27], v[72:75], v[160:163], v[24:27]
	v_mfma_f32_16x16x32_bf16 v[12:15], v[64:67], v[168:171], v[12:15]
	v_mfma_f32_16x16x32_bf16 v[8:11], v[72:75], v[168:171], v[8:11]
	v_mfma_f32_16x16x32_bf16 v[60:63], v[68:71], v[84:87], v[60:63]
	v_mfma_f32_16x16x32_bf16 v[56:59], v[76:79], v[84:87], v[56:59]
	v_mfma_f32_16x16x32_bf16 v[44:47], v[68:71], v[92:95], v[44:47]
	v_mfma_f32_16x16x32_bf16 v[40:43], v[76:79], v[92:95], v[40:43]
	v_mfma_f32_16x16x32_bf16 v[28:31], v[68:71], v[164:167], v[28:31]
	v_mfma_f32_16x16x32_bf16 v[24:27], v[76:79], v[164:167], v[24:27]
	v_mfma_f32_16x16x32_bf16 v[12:15], v[68:71], v[172:175], v[12:15]
	v_mfma_f32_16x16x32_bf16 v[8:11], v[76:79], v[172:175], v[8:11]
	s_setprio 0
	s_barrier
	s_add_u32 s2, s2, 0x200080
	s_addc_u32 s3, s3, 0
	s_add_i32 s20, s20, s11
	v_lshl_add_u64 v[64:65], s[2:3], 0, v[194:195]
	s_mov_b32 m0, s20
	s_nop 0
	global_load_lds_dwordx4 v[64:65], off
	v_lshl_add_u64 v[64:65], s[2:3], 0, v[202:203]
	s_add_i32 m0, s20, 0x2000
	s_nop 0
	global_load_lds_dwordx4 v[64:65], off
	s_waitcnt vmcnt(6)
	s_barrier
	s_setprio 1
	v_mfma_f32_16x16x32_bf16 v[52:55], v[184:187], v[80:83], v[52:55]
	v_mfma_f32_16x16x32_bf16 v[48:51], v[212:215], v[80:83], v[48:51]
	v_mfma_f32_16x16x32_bf16 v[36:39], v[184:187], v[88:91], v[36:39]
	v_mfma_f32_16x16x32_bf16 v[32:35], v[212:215], v[88:91], v[32:35]
	v_mfma_f32_16x16x32_bf16 v[20:23], v[184:187], v[160:163], v[20:23]
	v_mfma_f32_16x16x32_bf16 v[16:19], v[212:215], v[160:163], v[16:19]
	v_mfma_f32_16x16x32_bf16 v[4:7], v[184:187], v[168:171], v[4:7]
	v_mfma_f32_16x16x32_bf16 v[0:3], v[212:215], v[168:171], v[0:3]
	v_mfma_f32_16x16x32_bf16 v[52:55], v[208:211], v[84:87], v[52:55]
	v_mfma_f32_16x16x32_bf16 v[48:51], v[216:219], v[84:87], v[48:51]
	v_mfma_f32_16x16x32_bf16 v[36:39], v[208:211], v[92:95], v[36:39]
	v_mfma_f32_16x16x32_bf16 v[32:35], v[216:219], v[92:95], v[32:35]
	v_mfma_f32_16x16x32_bf16 v[20:23], v[208:211], v[164:167], v[20:23]
	v_mfma_f32_16x16x32_bf16 v[16:19], v[216:219], v[164:167], v[16:19]
	v_mfma_f32_16x16x32_bf16 v[4:7], v[208:211], v[172:175], v[4:7]
	v_mfma_f32_16x16x32_bf16 v[0:3], v[216:219], v[172:175], v[0:3]
	s_setprio 0
	s_add_i32 s86, s86, 2
	s_add_u32 s42, s42, 0x100
	s_addc_u32 s43, s43, 0
	s_add_u32 s59, s59, 0x100
	s_addc_u32 s61, s61, 0
	s_cmpk_gt_u32 s86, 0x7d
	s_barrier
	s_cbranch_scc0 .LBB0_1168
	v_lshl_or_b32 v160, s66, 8, v236
	v_ashrrev_i32_e32 v161, 31, v160
	v_lshlrev_b64 v[64:65], 2, v[160:161]
	v_lshl_add_u32 v210, s70, 8, v234
	v_lshl_add_u64 v[68:69], s[50:51], 0, v[64:65]
	v_lshl_add_u64 v[76:77], s[54:55], 0, v[64:65]
	global_load_dwordx4 v[80:83], v[68:69], off offset:16 nt
	global_load_dwordx4 v[88:91], v[68:69], off nt
	global_load_dwordx4 v[84:87], v[76:77], off offset:16 nt
	global_load_dwordx4 v[92:95], v[76:77], off nt
	global_load_dwordx4 v[64:67], v[68:69], off offset:528 nt
	global_load_dwordx4 v[72:75], v[68:69], off offset:512 nt
	s_nop 0
	global_load_dwordx4 v[68:71], v[76:77], off offset:528 nt
	s_nop 0
	global_load_dwordx4 v[76:79], v[76:77], off offset:512 nt
	v_lshlrev_b64 v[160:161], 1, v[160:161]
	v_ashrrev_i32_e32 v211, 31, v210
	v_add_u32_e32 v214, 16, v210
	v_lshl_add_u64 v[212:213], s[46:47], 0, v[160:161]
	v_lshlrev_b64 v[238:239], 12, v[210:211]
	v_ashrrev_i32_e32 v215, 31, v214
	v_add_u32_e32 v218, 32, v210
	v_lshl_add_u64 v[208:209], s[44:45], 0, v[160:161]
	v_lshl_add_u64 v[160:161], v[212:213], 0, v[238:239]
	v_lshlrev_b64 v[228:229], 12, v[214:215]
	v_ashrrev_i32_e32 v219, 31, v218
	v_add_u32_e32 v220, 48, v210
	v_lshlrev_b64 v[222:223], 12, v[218:219]
	v_ashrrev_i32_e32 v221, 31, v220
	v_lshlrev_b64 v[216:217], 12, v[220:221]
	v_lshlrev_b64 v[230:231], 3, v[210:211]
	v_lshlrev_b64 v[224:225], 3, v[214:215]
	v_lshlrev_b64 v[218:219], 3, v[218:219]
	v_lshlrev_b64 v[214:215], 3, v[220:221]
	v_lshl_add_u64 v[250:251], s[48:49], 0, v[230:231]
	v_lshl_add_u64 v[232:233], s[48:49], 0, v[224:225]
	v_lshl_add_u64 v[226:227], s[48:49], 0, v[218:219]
	v_lshl_add_u64 v[220:221], s[48:49], 0, v[214:215]
	v_lshl_add_u64 v[238:239], v[208:209], 0, v[238:239]
	v_readlane_b32 s2, v255, 32
	v_readlane_b32 s3, v255, 33
	s_waitcnt vmcnt(0)
	global_load_dwordx4 v[246:249], v[160:161], off nt
	global_load_dwordx4 v[184:187], v[160:161], off offset:256 nt
	v_lshl_add_u64 v[160:161], v[212:213], 0, v[228:229]
	global_load_dwordx4 v[180:183], v[160:161], off nt
	global_load_dwordx4 v[176:179], v[160:161], off offset:256 nt
	v_lshl_add_u64 v[160:161], v[212:213], 0, v[222:223]
	global_load_dwordx4 v[172:175], v[160:161], off nt
	global_load_dwordx4 v[168:171], v[160:161], off offset:256 nt
	v_lshl_add_u64 v[160:161], v[212:213], 0, v[216:217]
	global_load_dwordx4 v[164:167], v[160:161], off nt
	s_nop 0
	global_load_dwordx4 v[160:163], v[160:161], off offset:256 nt
	s_nop 0
	global_load_dwordx2 v[220:221], v[220:221], off
	s_nop 0
	global_load_dwordx2 v[226:227], v[226:227], off
	s_nop 0
	global_load_dwordx2 v[232:233], v[232:233], off
	s_nop 0
	global_load_dwordx2 v[250:251], v[250:251], off
	s_waitcnt vmcnt(0)
	s_nop 0
	v_pk_mul_f32 v[250:251], v[250:251], s[28:29] op_sel_hi:[1,0]
	s_nop 0
	v_fma_f32 v211, -v250, v250, v251
	v_max_f32_e32 v211, 0, v211
	v_add_f32_e32 v211, 0x3727c5ac, v211
	v_cmp_gt_f32_e32 vcc, s13, v211
	v_mul_f32_e32 v240, 0x4b800000, v211
	v_lshlrev_b32_e32 v251, 16, v247
	v_cndmask_b32_e32 v211, v211, v240, vcc
	v_rsq_f32_e32 v211, v211
	v_and_b32_e32 v247, 0xffff0000, v247
	v_lshlrev_b32_e32 v252, 16, v248
	v_and_b32_e32 v248, 0xffff0000, v248
	v_mul_f32_e32 v240, 0x45800000, v211
	v_cndmask_b32_e32 v211, v211, v240, vcc
	v_lshlrev_b32_e32 v240, 16, v246
	v_sub_f32_e32 v240, v240, v250
	v_mul_f32_e32 v240, v240, v211
	v_and_b32_e32 v246, 0xffff0000, v246
	v_fma_f32 v240, v88, v240, v92
	v_fmamk_f32 v156, v240, 0x3fb504f3, v156
	v_sub_f32_e32 v240, v246, v250
	v_mul_f32_e32 v240, v240, v211
	v_fma_f32 v240, v89, v240, v93
	v_fmamk_f32 v157, v240, 0x3fb504f3, v157
	v_sub_f32_e32 v240, v251, v250
	v_mul_f32_e32 v240, v240, v211
	v_fma_f32 v240, v90, v240, v94
	v_fmamk_f32 v158, v240, 0x3fb504f3, v158
	v_sub_f32_e32 v240, v247, v250
	v_mul_f32_e32 v240, v240, v211
	v_fma_f32 v240, v91, v240, v95
	v_fmac_f32_e32 v159, 0x3fb504f3, v240
	v_sub_f32_e32 v240, v252, v250
	v_mul_f32_e32 v240, v240, v211
	v_fma_f32 v240, v80, v240, v84
	v_fmamk_f32 v152, v240, 0x3fb504f3, v152
	v_sub_f32_e32 v240, v248, v250
	v_mul_f32_e32 v240, v240, v211
	v_lshlrev_b32_e32 v253, 16, v249
	v_fma_f32 v240, v81, v240, v85
	v_fmamk_f32 v153, v240, 0x3fb504f3, v153
	v_sub_f32_e32 v240, v253, v250
	v_mul_f32_e32 v240, v240, v211
	v_and_b32_e32 v249, 0xffff0000, v249
	v_fma_f32 v240, v82, v240, v86
	v_fmamk_f32 v154, v240, 0x3fb504f3, v154
	v_sub_f32_e32 v240, v249, v250
	v_mul_f32_e32 v240, v240, v211
	v_fma_f32 v240, v83, v240, v87
	v_fmac_f32_e32 v155, 0x3fb504f3, v240
	v_lshlrev_b32_e32 v240, 16, v184
	v_and_b32_e32 v184, 0xffff0000, v184
	v_sub_f32_e32 v184, v184, v250
	v_cvt_pk_bf16_f32 v246, v156, v157
	v_mul_f32_e32 v184, v184, v211
	v_cvt_pk_bf16_f32 v247, v158, v159
	v_cvt_pk_bf16_f32 v248, v152, v153
	v_cvt_pk_bf16_f32 v249, v154, v155
	global_store_dwordx4 v[238:239], v[246:249], off
	v_fma_f32 v184, v73, v184, v77
	v_fmamk_f32 v149, v184, 0x3fb504f3, v149
	v_lshlrev_b32_e32 v246, 16, v185
	v_sub_f32_e32 v184, v246, v250
	v_mul_f32_e32 v184, v184, v211
	v_and_b32_e32 v185, 0xffff0000, v185
	v_fma_f32 v184, v74, v184, v78
	v_fmamk_f32 v150, v184, 0x3fb504f3, v150
	v_sub_f32_e32 v184, v185, v250
	v_mul_f32_e32 v184, v184, v211
	v_lshlrev_b32_e32 v247, 16, v186
	v_fma_f32 v184, v75, v184, v79
	v_fmac_f32_e32 v151, 0x3fb504f3, v184
	v_sub_f32_e32 v184, v247, v250
	v_mul_f32_e32 v184, v184, v211
	v_and_b32_e32 v186, 0xffff0000, v186
	v_fma_f32 v184, v64, v184, v68
	v_fmamk_f32 v144, v184, 0x3fb504f3, v144
	v_sub_f32_e32 v184, v186, v250
	v_mul_f32_e32 v184, v184, v211
	v_lshlrev_b32_e32 v248, 16, v187
	v_fma_f32 v184, v65, v184, v69
	v_fmamk_f32 v145, v184, 0x3fb504f3, v145
	v_sub_f32_e32 v184, v248, v250
	v_mul_f32_e32 v184, v184, v211
	v_and_b32_e32 v187, 0xffff0000, v187
	v_fma_f32 v184, v66, v184, v70
	v_sub_f32_e32 v240, v240, v250
	v_fmamk_f32 v146, v184, 0x3fb504f3, v146
	v_sub_f32_e32 v184, v187, v250
	v_mul_f32_e32 v240, v240, v211
	v_mul_f32_e32 v184, v184, v211
	v_fma_f32 v240, v72, v240, v76
	v_fma_f32 v184, v67, v184, v71
	v_fmamk_f32 v148, v240, 0x3fb504f3, v148
	v_fmac_f32_e32 v147, 0x3fb504f3, v184
	v_cvt_pk_bf16_f32 v184, v148, v149
	v_cvt_pk_bf16_f32 v185, v150, v151
	v_cvt_pk_bf16_f32 v186, v144, v145
	v_cvt_pk_bf16_f32 v187, v146, v147
	global_store_dwordx4 v[238:239], v[184:187], off offset:256
	s_andn2_b64 vcc, exec, s[2:3]
	s_nop 0
	v_cndmask_b32_e64 v184, 0, 1, s[2:3]
	v_cmp_ne_u32_e64 s[42:43], 1, v184
	s_cbranch_vccnz .LBB0_1173
	v_mul_f32_e32 v184, v157, v157
	v_fmac_f32_e32 v184, v156, v156
	v_add_f32_e32 v156, 0, v156
	v_add_f32_e32 v156, v157, v156
	v_fmac_f32_e32 v184, v158, v158
	v_add_f32_e32 v156, v158, v156
	v_fmac_f32_e32 v184, v159, v159
	v_add_f32_e32 v156, v159, v156
	v_fmac_f32_e32 v184, v152, v152
	v_add_f32_e32 v152, v152, v156
	v_fmac_f32_e32 v184, v153, v153
	v_add_f32_e32 v152, v153, v152
	v_fmac_f32_e32 v184, v154, v154
	v_add_f32_e32 v152, v154, v152
	v_fmac_f32_e32 v184, v155, v155
	v_add_f32_e32 v152, v155, v152
	v_fmac_f32_e32 v184, v148, v148
	v_add_f32_e32 v148, v148, v152
	v_fmac_f32_e32 v184, v149, v149
	v_add_f32_e32 v148, v149, v148
	v_fmac_f32_e32 v184, v150, v150
	v_add_f32_e32 v148, v150, v148
	v_fmac_f32_e32 v184, v151, v151
	v_add_f32_e32 v148, v151, v148
	v_and_b32_e32 v150, 64, v242
	v_add_f32_e32 v148, v144, v148
	v_xor_b32_e32 v149, 16, v242
	v_add_u32_e32 v150, 64, v150
	v_fmac_f32_e32 v184, v144, v144
	v_add_f32_e32 v148, v145, v148
	v_cmp_lt_i32_e32 vcc, v149, v150
	v_fmac_f32_e32 v184, v145, v145
	v_add_f32_e32 v148, v146, v148
	v_cndmask_b32_e32 v149, v242, v149, vcc
	v_fmac_f32_e32 v184, v146, v146
	v_add_f32_e32 v148, v147, v148
	v_lshlrev_b32_e32 v149, 2, v149
	v_fmac_f32_e32 v184, v147, v147
	ds_bpermute_b32 v151, v149, v148
	ds_bpermute_b32 v146, v149, v184
	v_xor_b32_e32 v145, 32, v242
	v_cmp_lt_i32_e32 vcc, v145, v150
	s_waitcnt lgkmcnt(0)
	v_add_f32_e32 v144, v148, v151
	v_cndmask_b32_e32 v145, v242, v145, vcc
	v_lshlrev_b32_e32 v147, 2, v145
	v_add_f32_e32 v146, v184, v146
	ds_bpermute_b32 v145, v147, v144
	ds_bpermute_b32 v147, v147, v146
	s_and_saveexec_b64 s[2:3], s[38:39]
	s_cbranch_execz .LBB0_1172
	s_waitcnt lgkmcnt(0)
	v_add_f32_e32 v146, v146, v147
	v_add_f32_e32 v147, v144, v145
	v_lshl_add_u64 v[144:145], s[56:57], 0, v[230:231]
	global_atomic_add_f32 v[144:145], v147, off
	global_atomic_add_f32 v[144:145], v146, off offset:4

.LBB0_1262:
	s_or_b64 exec, exec, s[2:3]
	s_waitcnt vmcnt(3)
	v_lshlrev_b32_e32 v126, 16, v76
	v_and_b32_e32 v127, 0xffff0000, v76
	v_add_f32_e32 v142, 0, v126
	v_lshlrev_b32_e32 v76, 16, v77
	v_add_f32_e32 v142, v142, v127
	v_and_b32_e32 v77, 0xffff0000, v77
	v_add_f32_e32 v142, v142, v76
	v_lshlrev_b32_e32 v128, 16, v78
	v_add_f32_e32 v142, v142, v77
	v_and_b32_e32 v129, 0xffff0000, v78
	v_add_f32_e32 v142, v142, v128
	v_lshlrev_b32_e32 v78, 16, v79
	v_add_f32_e32 v142, v142, v129
	v_and_b32_e32 v79, 0xffff0000, v79
	v_add_f32_e32 v142, v142, v78
	s_waitcnt vmcnt(2)
	v_lshlrev_b32_e32 v130, 16, v72
	v_add_f32_e32 v142, v142, v79
	v_and_b32_e32 v131, 0xffff0000, v72
	v_add_f32_e32 v142, v142, v130
	v_lshlrev_b32_e32 v72, 16, v73
	v_add_f32_e32 v142, v142, v131
	v_and_b32_e32 v73, 0xffff0000, v73
	v_add_f32_e32 v142, v142, v72
	v_lshlrev_b32_e32 v132, 16, v74
	v_add_f32_e32 v142, v142, v73
	v_and_b32_e32 v133, 0xffff0000, v74
	v_add_f32_e32 v142, v142, v132
	v_lshlrev_b32_e32 v74, 16, v75
	v_add_f32_e32 v142, v142, v133
	v_and_b32_e32 v75, 0xffff0000, v75
	v_add_f32_e32 v142, v142, v74
	s_waitcnt vmcnt(1)
	v_lshlrev_b32_e32 v134, 16, v68
	v_add_f32_e32 v142, v142, v75
	v_and_b32_e32 v135, 0xffff0000, v68
	v_add_f32_e32 v142, v142, v134
	v_lshlrev_b32_e32 v68, 16, v69
	v_add_f32_e32 v142, v142, v135
	v_and_b32_e32 v69, 0xffff0000, v69
	v_add_f32_e32 v142, v142, v68
	v_lshlrev_b32_e32 v136, 16, v70
	v_add_f32_e32 v142, v142, v69
	v_and_b32_e32 v137, 0xffff0000, v70
	v_add_f32_e32 v142, v142, v136
	v_lshlrev_b32_e32 v70, 16, v71
	v_add_f32_e32 v142, v142, v137
	v_and_b32_e32 v71, 0xffff0000, v71
	v_add_f32_e32 v142, v142, v70
	s_waitcnt vmcnt(0)
	v_lshlrev_b32_e32 v138, 16, v64
	v_add_f32_e32 v142, v142, v71
	v_and_b32_e32 v139, 0xffff0000, v64
	v_add_f32_e32 v142, v142, v138
	v_lshlrev_b32_e32 v64, 16, v65
	v_add_f32_e32 v142, v142, v139
	v_and_b32_e32 v65, 0xffff0000, v65
	v_add_f32_e32 v142, v142, v64
	v_lshlrev_b32_e32 v140, 16, v66
	v_add_f32_e32 v142, v142, v65
	v_and_b32_e32 v141, 0xffff0000, v66
	v_add_f32_e32 v142, v142, v140
	v_lshlrev_b32_e32 v66, 16, v67
	v_add_f32_e32 v142, v142, v141
	v_and_b32_e32 v67, 0xffff0000, v67
	v_add_f32_e32 v142, v142, v66
	v_add_f32_e32 v142, v142, v67
	ds_bpermute_b32 v143, v120, v142
	v_lshlrev_b64 v[118:119], 13, v[118:119]
	s_waitcnt lgkmcnt(0)
	v_add_f32_e32 v142, v142, v143
	ds_bpermute_b32 v143, v121, v142
	s_waitcnt lgkmcnt(0)
	v_add_f32_e32 v142, v142, v143
	ds_bpermute_b32 v143, v122, v142
	s_waitcnt lgkmcnt(0)
	v_add_f32_e32 v142, v142, v143
	ds_bpermute_b32 v143, v123, v142
	s_waitcnt lgkmcnt(0)
	v_add_f32_e32 v142, v142, v143
	ds_bpermute_b32 v143, v124, v142
	s_waitcnt lgkmcnt(0)
	v_add_f32_e32 v142, v142, v143
	ds_bpermute_b32 v143, v125, v142
	s_waitcnt lgkmcnt(0)
	v_add_f32_e32 v142, v142, v143
	v_mul_f32_e32 v142, 0x3a000000, v142
	v_pk_add_f32 v[126:127], v[126:127], v[142:143] op_sel_hi:[1,0] neg_lo:[0,1] neg_hi:[0,1]
	v_pk_add_f32 v[76:77], v[76:77], v[142:143] op_sel_hi:[1,0] neg_lo:[0,1] neg_hi:[0,1]
	v_pk_mul_f32 v[144:145], v[126:127], v[126:127]
	v_pk_mul_f32 v[146:147], v[76:77], v[76:77]
	v_add_f32_e32 v144, v144, v145
	v_pk_add_f32 v[128:129], v[128:129], v[142:143] op_sel_hi:[1,0] neg_lo:[0,1] neg_hi:[0,1]
	v_add_f32_e32 v144, v146, v144
	v_pk_mul_f32 v[148:149], v[128:129], v[128:129]
	v_add_f32_e32 v144, v147, v144
	v_pk_add_f32 v[78:79], v[78:79], v[142:143] op_sel_hi:[1,0] neg_lo:[0,1] neg_hi:[0,1]
	v_add_f32_e32 v144, v148, v144
	v_pk_mul_f32 v[150:151], v[78:79], v[78:79]
	v_add_f32_e32 v144, v149, v144
	v_pk_add_f32 v[130:131], v[130:131], v[142:143] op_sel_hi:[1,0] neg_lo:[0,1] neg_hi:[0,1]
	v_add_f32_e32 v144, v150, v144
	v_pk_mul_f32 v[152:153], v[130:131], v[130:131]
	v_add_f32_e32 v144, v151, v144
	v_pk_add_f32 v[72:73], v[72:73], v[142:143] op_sel_hi:[1,0] neg_lo:[0,1] neg_hi:[0,1]
	v_add_f32_e32 v144, v152, v144
	v_pk_mul_f32 v[154:155], v[72:73], v[72:73]
	v_add_f32_e32 v144, v153, v144
	v_pk_add_f32 v[132:133], v[132:133], v[142:143] op_sel_hi:[1,0] neg_lo:[0,1] neg_hi:[0,1]
	v_add_f32_e32 v144, v154, v144
	v_pk_mul_f32 v[156:157], v[132:133], v[132:133]
	v_add_f32_e32 v144, v155, v144
	v_pk_add_f32 v[74:75], v[74:75], v[142:143] op_sel_hi:[1,0] neg_lo:[0,1] neg_hi:[0,1]
	v_add_f32_e32 v144, v156, v144
	v_pk_mul_f32 v[158:159], v[74:75], v[74:75]
	v_add_f32_e32 v144, v157, v144
	v_pk_add_f32 v[134:135], v[134:135], v[142:143] op_sel_hi:[1,0] neg_lo:[0,1] neg_hi:[0,1]
	v_add_f32_e32 v144, v158, v144
	v_pk_mul_f32 v[160:161], v[134:135], v[134:135]
	v_add_f32_e32 v144, v159, v144
	v_pk_add_f32 v[68:69], v[68:69], v[142:143] op_sel_hi:[1,0] neg_lo:[0,1] neg_hi:[0,1]
	v_add_f32_e32 v144, v160, v144
	v_pk_mul_f32 v[162:163], v[68:69], v[68:69]
	v_add_f32_e32 v144, v161, v144
	v_pk_add_f32 v[136:137], v[136:137], v[142:143] op_sel_hi:[1,0] neg_lo:[0,1] neg_hi:[0,1]
	v_add_f32_e32 v144, v162, v144
	v_pk_mul_f32 v[164:165], v[136:137], v[136:137]
	v_add_f32_e32 v144, v163, v144
	v_pk_add_f32 v[70:71], v[70:71], v[142:143] op_sel_hi:[1,0] neg_lo:[0,1] neg_hi:[0,1]
	v_add_f32_e32 v144, v164, v144
	v_pk_mul_f32 v[166:167], v[70:71], v[70:71]
	v_add_f32_e32 v144, v165, v144
	v_pk_add_f32 v[138:139], v[138:139], v[142:143] op_sel_hi:[1,0] neg_lo:[0,1] neg_hi:[0,1]
	v_add_f32_e32 v144, v166, v144
	v_pk_mul_f32 v[168:169], v[138:139], v[138:139]
	v_add_f32_e32 v144, v167, v144
	v_pk_add_f32 v[170:171], v[64:65], v[142:143] op_sel_hi:[1,0] neg_lo:[0,1] neg_hi:[0,1]
	v_add_f32_e32 v144, v168, v144
	v_pk_mul_f32 v[64:65], v[170:171], v[170:171]
	v_add_f32_e32 v144, v169, v144
	v_pk_add_f32 v[140:141], v[140:141], v[142:143] op_sel_hi:[1,0] neg_lo:[0,1] neg_hi:[0,1]
	v_add_f32_e32 v64, v64, v144
	v_pk_mul_f32 v[172:173], v[140:141], v[140:141]
	v_add_f32_e32 v64, v65, v64
	v_pk_add_f32 v[142:143], v[66:67], v[142:143] op_sel_hi:[1,0] neg_lo:[0,1] neg_hi:[0,1]
	v_add_f32_e32 v64, v172, v64
	v_pk_mul_f32 v[66:67], v[142:143], v[142:143]
	v_add_f32_e32 v64, v173, v64
	v_add_f32_e32 v64, v66, v64
	v_add_f32_e32 v64, v67, v64
	ds_bpermute_b32 v65, v120, v64
	s_waitcnt lgkmcnt(0)
	v_add_f32_e32 v64, v64, v65
	ds_bpermute_b32 v65, v121, v64
	s_waitcnt lgkmcnt(0)
	v_add_f32_e32 v64, v64, v65
	ds_bpermute_b32 v65, v122, v64
	s_waitcnt lgkmcnt(0)
	v_add_f32_e32 v64, v64, v65
	ds_bpermute_b32 v65, v123, v64
	s_waitcnt lgkmcnt(0)
	v_add_f32_e32 v64, v64, v65
	ds_bpermute_b32 v65, v124, v64
	s_waitcnt lgkmcnt(0)
	v_add_f32_e32 v64, v64, v65
	ds_bpermute_b32 v65, v125, v64
	s_waitcnt lgkmcnt(0)
	v_add_f32_e32 v64, v64, v65
	v_fmamk_f32 v64, v64, 0x3a000000, v243
	v_mul_f32_e32 v65, 0x4b800000, v64
	v_cmp_gt_f32_e64 s[38:39], s13, v64
	s_nop 1
	v_cndmask_b32_e64 v64, v64, v65, s[38:39]
	v_rsq_f32_e32 v64, v64
	s_nop 0
	v_mul_f32_e32 v65, 0x45800000, v64
	v_cndmask_b32_e64 v144, v64, v65, s[38:39]
	v_pk_mul_f32 v[64:65], v[126:127], v[144:145] op_sel_hi:[1,0]
	v_pk_mul_f32 v[66:67], v[76:77], v[144:145] op_sel_hi:[1,0]
	v_pk_fma_f32 v[64:65], v[4:5], v[64:65], v[12:13]
	v_pk_fma_f32 v[66:67], v[6:7], v[66:67], v[14:15]
	v_lshl_add_u64 v[76:77], v[82:83], 0, v[118:119]
	global_store_dwordx4 v[76:77], v[64:67], off nt
	s_nop 1
	v_pk_mul_f32 v[64:65], v[128:129], v[144:145] op_sel_hi:[1,0]
	v_pk_mul_f32 v[66:67], v[78:79], v[144:145] op_sel_hi:[1,0]
	v_pk_fma_f32 v[64:65], v[0:1], v[64:65], v[8:9]
	v_pk_fma_f32 v[66:67], v[2:3], v[66:67], v[10:11]
	global_store_dwordx4 v[76:77], v[64:67], off offset:16 nt
	s_nop 1
	v_pk_mul_f32 v[64:65], v[130:131], v[144:145] op_sel_hi:[1,0]
	v_pk_mul_f32 v[66:67], v[72:73], v[144:145] op_sel_hi:[1,0]
	v_pk_fma_f32 v[64:65], v[20:21], v[64:65], v[28:29]
	v_pk_fma_f32 v[66:67], v[22:23], v[66:67], v[30:31]
	global_store_dwordx4 v[76:77], v[64:67], off offset:2048 nt
	s_nop 1
	v_pk_mul_f32 v[64:65], v[132:133], v[144:145] op_sel_hi:[1,0]
	v_pk_mul_f32 v[66:67], v[74:75], v[144:145] op_sel_hi:[1,0]
	v_pk_fma_f32 v[64:65], v[16:17], v[64:65], v[24:25]
	v_pk_fma_f32 v[66:67], v[18:19], v[66:67], v[26:27]
	global_store_dwordx4 v[76:77], v[64:67], off offset:2064 nt
	s_nop 1
	v_pk_mul_f32 v[64:65], v[134:135], v[144:145] op_sel_hi:[1,0]
	v_pk_mul_f32 v[66:67], v[68:69], v[144:145] op_sel_hi:[1,0]
	v_add_co_u32_e64 v68, s[38:39], s81, v76
	v_pk_fma_f32 v[66:67], v[38:39], v[66:67], v[46:47]
	v_pk_fma_f32 v[64:65], v[36:37], v[64:65], v[44:45]
	v_addc_co_u32_e64 v69, s[38:39], 0, v77, s[38:39]
	global_store_dwordx4 v[68:69], v[64:67], off nt
	s_nop 1
	v_pk_mul_f32 v[64:65], v[136:137], v[144:145] op_sel_hi:[1,0]
	v_pk_mul_f32 v[66:67], v[70:71], v[144:145] op_sel_hi:[1,0]
	v_pk_fma_f32 v[64:65], v[32:33], v[64:65], v[40:41]
	v_pk_fma_f32 v[66:67], v[34:35], v[66:67], v[42:43]
	global_store_dwordx4 v[68:69], v[64:67], off offset:16 nt
	s_nop 1
	v_pk_mul_f32 v[64:65], v[138:139], v[144:145] op_sel_hi:[1,0]
	v_pk_mul_f32 v[66:67], v[170:171], v[144:145] op_sel_hi:[1,0]
	v_pk_fma_f32 v[64:65], v[52:53], v[64:65], v[60:61]
	v_pk_fma_f32 v[66:67], v[54:55], v[66:67], v[62:63]
	global_store_dwordx4 v[68:69], v[64:67], off offset:2048 nt
	s_nop 1
	v_pk_mul_f32 v[64:65], v[140:141], v[144:145] op_sel_hi:[1,0]
	v_pk_mul_f32 v[66:67], v[142:143], v[144:145] op_sel_hi:[1,0]
	v_pk_fma_f32 v[64:65], v[48:49], v[64:65], v[56:57]
	v_pk_fma_f32 v[66:67], v[50:51], v[66:67], v[58:59]
	global_store_dwordx4 v[68:69], v[64:67], off offset:2064 nt
	s_and_saveexec_b64 s[2:3], vcc
	s_cbranch_execz .LBB0_1259
	v_add_f32_e32 v64, 0, v84
	v_add_f32_e32 v64, v85, v64
	v_add_f32_e32 v64, v88, v64
	v_add_f32_e32 v64, v89, v64
	v_add_f32_e32 v64, v90, v64
	v_add_f32_e32 v64, v91, v64
	v_add_f32_e32 v64, v92, v64
	v_add_f32_e32 v64, v93, v64
	v_add_f32_e32 v64, v94, v64
	v_add_f32_e32 v64, v95, v64
	v_add_f32_e32 v64, v96, v64
	v_add_f32_e32 v64, v97, v64
	v_add_f32_e32 v64, v98, v64
	v_add_f32_e32 v64, v99, v64
	v_add_f32_e32 v64, v100, v64
	v_add_f32_e32 v64, v101, v64
	v_add_f32_e32 v64, v102, v64
	v_add_f32_e32 v64, v103, v64
	v_add_f32_e32 v64, v104, v64
	v_add_f32_e32 v64, v105, v64
	v_add_f32_e32 v64, v106, v64
	v_add_f32_e32 v64, v107, v64
	v_add_f32_e32 v64, v108, v64
	v_add_f32_e32 v64, v109, v64
	v_add_f32_e32 v64, v110, v64
	v_add_f32_e32 v64, v111, v64
	v_add_f32_e32 v64, v112, v64
	v_add_f32_e32 v64, v113, v64
	v_add_f32_e32 v64, v114, v64
	v_add_f32_e32 v64, v115, v64
	v_add_f32_e32 v64, v116, v64
	v_add_f32_e32 v64, v117, v64
	ds_bpermute_b32 v65, v120, v64
	s_waitcnt lgkmcnt(0)
	v_add_f32_e32 v64, v64, v65
	ds_bpermute_b32 v65, v121, v64
	s_waitcnt lgkmcnt(0)
	v_add_f32_e32 v64, v64, v65
	ds_bpermute_b32 v65, v122, v64
	s_waitcnt lgkmcnt(0)
	v_add_f32_e32 v64, v64, v65
	ds_bpermute_b32 v65, v123, v64
	s_waitcnt lgkmcnt(0)
	v_add_f32_e32 v64, v64, v65
	ds_bpermute_b32 v65, v124, v64
	s_waitcnt lgkmcnt(0)
	v_add_f32_e32 v64, v64, v65
	ds_bpermute_b32 v65, v125, v64
	s_waitcnt lgkmcnt(0)
	v_add_f32_e32 v64, v64, v65
	v_mul_f32_e32 v64, 0x3a000000, v64
	v_pk_add_f32 v[66:67], v[84:85], v[64:65] op_sel_hi:[1,0] neg_lo:[0,1] neg_hi:[0,1]
	v_pk_add_f32 v[68:69], v[88:89], v[64:65] op_sel_hi:[1,0] neg_lo:[0,1] neg_hi:[0,1]
	v_pk_mul_f32 v[136:137], v[66:67], v[66:67]
	v_pk_mul_f32 v[138:139], v[68:69], v[68:69]
	v_add_f32_e32 v136, v136, v137
	v_pk_add_f32 v[70:71], v[90:91], v[64:65] op_sel_hi:[1,0] neg_lo:[0,1] neg_hi:[0,1]
	v_add_f32_e32 v136, v138, v136
	v_pk_mul_f32 v[140:141], v[70:71], v[70:71]
	v_add_f32_e32 v136, v139, v136
	v_pk_add_f32 v[72:73], v[92:93], v[64:65] op_sel_hi:[1,0] neg_lo:[0,1] neg_hi:[0,1]
	v_add_f32_e32 v136, v140, v136
	v_pk_mul_f32 v[142:143], v[72:73], v[72:73]
	v_add_f32_e32 v136, v141, v136
	v_pk_add_f32 v[74:75], v[94:95], v[64:65] op_sel_hi:[1,0] neg_lo:[0,1] neg_hi:[0,1]
	v_add_f32_e32 v136, v142, v136
	v_pk_mul_f32 v[144:145], v[74:75], v[74:75]
	v_add_f32_e32 v136, v143, v136
	v_pk_add_f32 v[76:77], v[96:97], v[64:65] op_sel_hi:[1,0] neg_lo:[0,1] neg_hi:[0,1]
	v_add_f32_e32 v136, v144, v136
	v_pk_mul_f32 v[146:147], v[76:77], v[76:77]
	v_add_f32_e32 v136, v145, v136
	v_pk_add_f32 v[78:79], v[98:99], v[64:65] op_sel_hi:[1,0] neg_lo:[0,1] neg_hi:[0,1]
	v_add_f32_e32 v136, v146, v136
	v_pk_mul_f32 v[148:149], v[78:79], v[78:79]
	v_add_f32_e32 v136, v147, v136
	v_pk_add_f32 v[118:119], v[100:101], v[64:65] op_sel_hi:[1,0] neg_lo:[0,1] neg_hi:[0,1]
	v_add_f32_e32 v136, v148, v136
	v_pk_mul_f32 v[150:151], v[118:119], v[118:119]
	v_add_f32_e32 v136, v149, v136
	v_pk_add_f32 v[126:127], v[102:103], v[64:65] op_sel_hi:[1,0] neg_lo:[0,1] neg_hi:[0,1]
	v_add_f32_e32 v136, v150, v136
	v_pk_mul_f32 v[152:153], v[126:127], v[126:127]
	v_add_f32_e32 v136, v151, v136
	v_pk_add_f32 v[128:129], v[104:105], v[64:65] op_sel_hi:[1,0] neg_lo:[0,1] neg_hi:[0,1]
	v_add_f32_e32 v136, v152, v136
	v_pk_mul_f32 v[154:155], v[128:129], v[128:129]
	v_add_f32_e32 v136, v153, v136
	v_pk_add_f32 v[130:131], v[106:107], v[64:65] op_sel_hi:[1,0] neg_lo:[0,1] neg_hi:[0,1]
	v_add_f32_e32 v136, v154, v136
	v_pk_mul_f32 v[156:157], v[130:131], v[130:131]
	v_add_f32_e32 v136, v155, v136
	v_pk_add_f32 v[132:133], v[108:109], v[64:65] op_sel_hi:[1,0] neg_lo:[0,1] neg_hi:[0,1]
	v_add_f32_e32 v136, v156, v136
	v_pk_mul_f32 v[158:159], v[132:133], v[132:133]
	v_add_f32_e32 v136, v157, v136
	v_pk_add_f32 v[134:135], v[110:111], v[64:65] op_sel_hi:[1,0] neg_lo:[0,1] neg_hi:[0,1]
	v_add_f32_e32 v136, v158, v136
	v_pk_mul_f32 v[160:161], v[134:135], v[134:135]
	v_add_f32_e32 v136, v159, v136
	v_pk_add_f32 v[162:163], v[112:113], v[64:65] op_sel_hi:[1,0] neg_lo:[0,1] neg_hi:[0,1]
	v_add_f32_e32 v136, v160, v136
	v_pk_mul_f32 v[164:165], v[162:163], v[162:163]
	v_add_f32_e32 v136, v161, v136
	v_pk_add_f32 v[166:167], v[114:115], v[64:65] op_sel_hi:[1,0] neg_lo:[0,1] neg_hi:[0,1]
	v_add_f32_e32 v136, v164, v136
	v_pk_mul_f32 v[168:169], v[166:167], v[166:167]
	v_add_f32_e32 v136, v165, v136
	v_pk_add_f32 v[170:171], v[116:117], v[64:65] op_sel_hi:[1,0] neg_lo:[0,1] neg_hi:[0,1]
	v_add_f32_e32 v136, v168, v136
	v_pk_mul_f32 v[64:65], v[170:171], v[170:171]
	v_add_f32_e32 v136, v169, v136
	v_add_f32_e32 v64, v64, v136
	v_add_f32_e32 v64, v65, v64
	ds_bpermute_b32 v65, v120, v64
	s_waitcnt lgkmcnt(0)
	v_add_f32_e32 v64, v64, v65
	ds_bpermute_b32 v65, v121, v64
	s_waitcnt lgkmcnt(0)
	v_add_f32_e32 v64, v64, v65
	ds_bpermute_b32 v65, v122, v64
	s_waitcnt lgkmcnt(0)
	v_add_f32_e32 v64, v64, v65
	ds_bpermute_b32 v65, v123, v64
	s_waitcnt lgkmcnt(0)
	v_add_f32_e32 v64, v64, v65
	ds_bpermute_b32 v65, v124, v64
	s_waitcnt lgkmcnt(0)
	v_add_f32_e32 v64, v64, v65
	ds_bpermute_b32 v65, v125, v64
	s_waitcnt lgkmcnt(0)
	v_add_f32_e32 v64, v64, v65
	v_fmamk_f32 v64, v64, 0x3a000000, v243
	v_mul_f32_e32 v65, 0x4b800000, v64
	v_cmp_gt_f32_e32 vcc, s13, v64
	s_nop 1
	v_cndmask_b32_e32 v64, v64, v65, vcc
	v_rsq_f32_e32 v138, v64
	v_lshlrev_b64 v[64:65], 13, v[86:87]
	v_lshl_add_u64 v[136:137], v[82:83], 0, v[64:65]
	v_mul_f32_e32 v64, 0x45800000, v138
	v_cndmask_b32_e32 v138, v138, v64, vcc
	v_pk_mul_f32 v[64:65], v[66:67], v[138:139] op_sel_hi:[1,0]
	v_pk_mul_f32 v[66:67], v[68:69], v[138:139] op_sel_hi:[1,0]
	v_pk_mul_f32 v[68:69], v[70:71], v[138:139] op_sel_hi:[1,0]
	v_pk_mul_f32 v[70:71], v[72:73], v[138:139] op_sel_hi:[1,0]
	v_pk_mul_f32 v[72:73], v[74:75], v[138:139] op_sel_hi:[1,0]
	v_pk_mul_f32 v[74:75], v[76:77], v[138:139] op_sel_hi:[1,0]
	v_pk_mul_f32 v[76:77], v[78:79], v[138:139] op_sel_hi:[1,0]
	v_pk_mul_f32 v[78:79], v[118:119], v[138:139] op_sel_hi:[1,0]
	v_pk_fma_f32 v[66:67], v[6:7], v[66:67], v[14:15]
	v_pk_fma_f32 v[64:65], v[4:5], v[64:65], v[12:13]
	v_pk_fma_f32 v[68:69], v[0:1], v[68:69], v[8:9]
	v_pk_mul_f32 v[118:119], v[126:127], v[138:139] op_sel_hi:[1,0]
	v_pk_fma_f32 v[70:71], v[2:3], v[70:71], v[10:11]
	v_pk_fma_f32 v[74:75], v[22:23], v[74:75], v[30:31]
	v_pk_fma_f32 v[72:73], v[20:21], v[72:73], v[28:29]
	v_pk_fma_f32 v[78:79], v[18:19], v[78:79], v[26:27]
	v_pk_fma_f32 v[76:77], v[16:17], v[76:77], v[24:25]
	global_store_dwordx4 v[136:137], v[64:67], off nt
	global_store_dwordx4 v[136:137], v[68:71], off offset:16 nt
	global_store_dwordx4 v[136:137], v[72:75], off offset:2048 nt
	global_store_dwordx4 v[136:137], v[76:79], off offset:2064 nt
	v_pk_mul_f32 v[64:65], v[128:129], v[138:139] op_sel_hi:[1,0]
	v_add_co_u32_e32 v68, vcc, s81, v136
	v_pk_fma_f32 v[66:67], v[38:39], v[64:65], v[46:47]
	v_pk_fma_f32 v[64:65], v[36:37], v[118:119], v[44:45]
	v_addc_co_u32_e32 v69, vcc, 0, v137, vcc
	global_store_dwordx4 v[68:69], v[64:67], off nt
	s_nop 1
	v_pk_mul_f32 v[64:65], v[130:131], v[138:139] op_sel_hi:[1,0]
	v_pk_mul_f32 v[66:67], v[132:133], v[138:139] op_sel_hi:[1,0]
	v_pk_fma_f32 v[64:65], v[32:33], v[64:65], v[40:41]
	v_pk_fma_f32 v[66:67], v[34:35], v[66:67], v[42:43]
	global_store_dwordx4 v[68:69], v[64:67], off offset:16 nt
	s_nop 1
	v_pk_mul_f32 v[64:65], v[134:135], v[138:139] op_sel_hi:[1,0]
	v_pk_mul_f32 v[66:67], v[162:163], v[138:139] op_sel_hi:[1,0]
	v_pk_fma_f32 v[64:65], v[52:53], v[64:65], v[60:61]
	v_pk_fma_f32 v[66:67], v[54:55], v[66:67], v[62:63]
	global_store_dwordx4 v[68:69], v[64:67], off offset:2048 nt
	s_nop 1
	v_pk_mul_f32 v[64:65], v[166:167], v[138:139] op_sel_hi:[1,0]
	v_pk_mul_f32 v[66:67], v[170:171], v[138:139] op_sel_hi:[1,0]
	v_pk_fma_f32 v[64:65], v[48:49], v[64:65], v[56:57]
	v_pk_fma_f32 v[66:67], v[50:51], v[66:67], v[58:59]
	global_store_dwordx4 v[68:69], v[64:67], off offset:2064 nt
	s_branch .LBB0_1259
